# v11 + Q/K/Z epilogue stores as full 128-byte lines (DPP exchange between the lower and upper 8 lanes of each 16-lane row; 8 rows x 128 B per store instead of 16 rows x 64 B)
# speedup vs baseline: 1.0065x; 1.0065x over previous
;     __device__ __forceinline__ void operator()(const AccT& acc, const Unit& u, int wr, int wc, int fr, int fq) const {
;         const int kind = (u.pn + pn_off) >> 3, tile = (u.pn + pn_off) & 7;
;         bf16_t* base = Q + (size_t)kind * ((WS_K - WS_Q) / 2); if (kind == 2) base = Z;
;         const float* g = gq; if (kind == 1) g = gk; const float gs = kind == 0 ? C2 : 1.f;
;         f32x4 gv[2][2];
; #pragma unroll
;         for (int bj = 0; bj < 2; ++bj)
; #pragma unroll
;             for (int n = 0; n < 2; ++n) gv[bj][n] = (kind < 2) ? *(const f32x4*)(g + 32 * bj + 8 * fq + 4 * n) * gs : (f32x4){1.f, 1.f, 1.f, 1.f};
.LBB0_119:
	v_and_b32_e32 v248, 8, v215
	v_lshrrev_b32_e32 v248, 3, v248
	v_mul_i32_i24_e32 v248, 0xffff8040, v248
	v_ashrrev_i32_e32 v249, 31, v248
	v_add_u32_e32 v250, 0x8000, v248
	v_mov_b32_e32 v251, 0
	s_ashr_i32 s66, s64, 3
	s_cmp_eq_u32 s66, 1
	s_cselect_b32 s7, s21, s19
	s_cselect_b32 s6, s20, s18
	s_cmp_lt_u32 s64, 8
	s_cselect_b64 vcc, -1, 0
	v_cndmask_b32_e32 v164, 1.0, v179, vcc
	v_mov_b32_e32 v148, 1.0
	v_mov_b32_e32 v149, 1.0
	v_mov_b32_e32 v150, 1.0
	v_mov_b32_e32 v151, 1.0
	v_mov_b32_e32 v152, 1.0
	v_mov_b32_e32 v153, 1.0
	v_mov_b32_e32 v154, 1.0
	v_mov_b32_e32 v155, 1.0
	v_mov_b32_e32 v156, 1.0
	v_mov_b32_e32 v157, 1.0
	v_mov_b32_e32 v158, 1.0
	v_mov_b32_e32 v159, 1.0
	v_mov_b32_e32 v160, 1.0
	v_mov_b32_e32 v161, 1.0
	v_mov_b32_e32 v162, 1.0
	v_mov_b32_e32 v163, 1.0
	v_mov_b32_e32 v165, v164
	v_lshl_add_u64 v[166:167], s[6:7], 0, v[136:137]
	s_cmp_lt_i32 s66, 2
	s_cselect_b64 s[70:71], -1, 0
	s_cbranch_scc0 .Lqk_nog
	global_load_dwordx4 v[150:153], v[166:167], off
	global_load_dwordx4 v[184:187], v[166:167], off offset:16
	global_load_dwordx4 v[158:161], v[166:167], off offset:128
	global_load_dwordx4 v[188:191], v[166:167], off offset:144
	s_waitcnt vmcnt(0)
	v_pk_mul_f32 v[150:151], v[164:165], v[150:151]
	v_pk_mul_f32 v[152:153], v[164:165], v[152:153]
	v_pk_mul_f32 v[148:149], v[164:165], v[184:185]
	v_pk_mul_f32 v[156:157], v[164:165], v[186:187]
	v_pk_mul_f32 v[158:159], v[164:165], v[158:159]
	v_pk_mul_f32 v[160:161], v[164:165], v[160:161]
	v_pk_mul_f32 v[154:155], v[164:165], v[188:189]
	v_pk_mul_f32 v[162:163], v[164:165], v[190:191]

; __device__ __forceinline__ u32x4 pack8(const f32x4& a, const f32x4& b) { u32x4 w; w.x = pk2(a[0], a[1]); w.y = pk2(a[2], a[3]); w.z = pk2(b[0], b[1]); w.w = pk2(b[2], b[3]); return w; }
;     __device__ __forceinline__ void operator()(const AccT& acc, const Unit& u, int wr, int wc, int fr, int fq) const {
;     ...
;         const int row0 = u.pm * 256 + wr * 64 + fr;
; #pragma unroll
;         for (int ai = 0; ai < 2; ++ai)
; #pragma unroll
;             for (int m = 0; m < 4; ++m) {
;                 const int row = row0 + ai * 128 + m * 16; float rs = 1.f;
;                 if (kind < 2) { float ss = 0.f;
; #pragma unroll
;                     for (int bj = 0; bj < 2; ++bj)
; #pragma unroll
;                         for (int n = 0; n < 2; ++n) { const f32x4 v = acc[ai][bj][m][n]; ss += (v[0] * v[0] + v[1] * v[1]) + (v[2] * v[2] + v[3] * v[3]); }
;                     ss += __shfl_xor(ss, 16); ss += __shfl_xor(ss, 32); rs = rsqrtf(ss * (1.f / 64.f) + EPS); }
;                 bf16_t* rp = base + (size_t)row * BR + tile * 256 + 64 * wc + 8 * fq;
; #pragma unroll
;                 for (int bj = 0; bj < 2; ++bj) { const f32x4 v0 = acc[ai][bj][m][0] * rs * gv[bj][0], v1 = acc[ai][bj][m][1] * rs * gv[bj][1];
;                     __builtin_nontemporal_store(pack8(v0, v1), (u32x4*)(rp + 32 * bj)); }
.LBB0_129:
	s_ashr_i32 s67, s66, 31
	s_lshl_b64 s[70:71], s[66:67], 27
	s_add_u32 s43, s34, s70
	s_addc_u32 s53, s35, s71
	s_cmp_eq_u32 s66, 2
	s_cselect_b32 s53, s29, s53
	s_cselect_b32 s43, s28, s43
	v_lshl_add_u32 v164, s62, 8, v139
	s_lshl_b32 s62, s64, 9
	s_and_b32 s62, s62, 0xe00
	s_add_u32 s43, s43, s62
	s_addc_u32 s53, s53, 0
	s_add_u32 s66, s43, s82
	s_addc_u32 s67, s53, 0
	v_lshlrev_b32_e32 v166, 1, v138
	v_mov_b32_e32 v167, v137
	v_ashrrev_i32_e32 v165, 31, v164
	v_lshl_add_u64 v[166:167], s[66:67], 0, v[166:167]
	v_lshlrev_b64 v[180:181], 12, v[164:165]
	v_pk_mul_f32 v[126:127], v[126:127], v[170:171] op_sel_hi:[1,0]
	v_pk_mul_f32 v[124:125], v[124:125], v[170:171] op_sel_hi:[1,0]
	v_pk_mul_f32 v[122:123], v[122:123], v[170:171] op_sel_hi:[1,0]
	v_pk_mul_f32 v[120:121], v[120:121], v[170:171] op_sel_hi:[1,0]
	v_lshl_add_u64 v[180:181], v[166:167], 0, v[180:181]
	v_pk_mul_f32 v[126:127], v[152:153], v[126:127]
	v_pk_mul_f32 v[124:125], v[150:151], v[124:125]
	v_pk_mul_f32 v[182:183], v[156:157], v[122:123]
	v_pk_mul_f32 v[122:123], v[148:149], v[120:121]
	v_cvt_pk_bf16_f32 v120, v124, v125
	v_cvt_pk_bf16_f32 v121, v126, v127
	v_pk_mul_f32 v[114:115], v[114:115], v[170:171] op_sel_hi:[1,0]
	v_pk_mul_f32 v[112:113], v[112:113], v[170:171] op_sel_hi:[1,0]
	v_cvt_pk_bf16_f32 v122, v122, v123
	v_cvt_pk_bf16_f32 v123, v182, v183
	v_mov_b32_e32 v240, v120
	v_mov_b32_e32 v241, v121
	v_mov_b32_e32 v242, v122
	v_mov_b32_e32 v243, v123
	v_pk_mul_f32 v[118:119], v[118:119], v[170:171] op_sel_hi:[1,0]
	v_pk_mul_f32 v[116:117], v[116:117], v[170:171] op_sel_hi:[1,0]
	v_pk_mul_f32 v[120:121], v[162:163], v[114:115]
	v_pk_mul_f32 v[114:115], v[154:155], v[112:113]
	s_and_b64 vcc, exec, s[6:7]
	v_pk_mul_f32 v[118:119], v[160:161], v[118:119]
	v_pk_mul_f32 v[116:117], v[158:159], v[116:117]
	s_nop 0
	v_cvt_pk_bf16_f32 v112, v116, v117
	v_cvt_pk_bf16_f32 v113, v118, v119
	v_cvt_pk_bf16_f32 v114, v114, v115
	v_cvt_pk_bf16_f32 v115, v120, v121
	v_mov_b32_e32 v244, v112
	v_mov_b32_e32 v245, v113
	v_mov_b32_e32 v246, v114
	v_mov_b32_e32 v247, v115
	v_mov_b32_dpp v244, v240 row_shl:8 row_mask:0xf bank_mask:0x3
	v_mov_b32_dpp v245, v241 row_shl:8 row_mask:0xf bank_mask:0x3
	v_mov_b32_dpp v246, v242 row_shl:8 row_mask:0xf bank_mask:0x3
	v_mov_b32_dpp v247, v243 row_shl:8 row_mask:0xf bank_mask:0x3
	v_mov_b32_dpp v240, v112 row_shr:8 row_mask:0xf bank_mask:0xc
	v_mov_b32_dpp v241, v113 row_shr:8 row_mask:0xf bank_mask:0xc
	v_mov_b32_dpp v242, v114 row_shr:8 row_mask:0xf bank_mask:0xc
	v_mov_b32_dpp v243, v115 row_shr:8 row_mask:0xf bank_mask:0xc
	v_lshl_add_u64 v[252:253], v[180:181], 0, v[248:249]
	v_lshl_add_u64 v[254:255], v[180:181], 0, v[250:251]
	global_store_dwordx4 v[252:253], v[240:243], off nt
	global_store_dwordx4 v[254:255], v[244:247], off nt
	s_cbranch_vccnz .LBB0_131
	s_nop 0
	v_pk_mul_f32 v[112:113], v[110:111], v[110:111]
	v_pk_mul_f32 v[114:115], v[108:109], v[108:109]
	s_nop 0
	v_pk_mov_b32 v[116:117], v[114:115], v[112:113] op_sel:[1,0]
	v_mov_b32_e32 v115, v113
	v_pk_add_f32 v[112:113], v[116:117], v[114:115]
	v_pk_mul_f32 v[114:115], v[106:107], v[106:107]
	v_pk_mul_f32 v[116:117], v[104:105], v[104:105]
	v_pk_add_f32 v[112:113], v[112:113], v[112:113] op_sel:[0,1] op_sel_hi:[1,0]
	v_pk_mov_b32 v[118:119], v[116:117], v[114:115] op_sel:[1,0]
	v_mov_b32_e32 v117, v115
	v_pk_add_f32 v[114:115], v[118:119], v[116:117]
	v_mul_f32_e32 v116, v96, v96
	v_mul_f32_e32 v117, v97, v97
	v_pk_add_f32 v[114:115], v[114:115], v[114:115] op_sel:[0,1] op_sel_hi:[1,0]
	v_mov_b32_e32 v113, v116
	v_mov_b32_e32 v115, v117
	v_pk_add_f32 v[112:113], v[112:113], v[114:115]
	v_mul_f32_e32 v114, v101, v101
	v_mul_f32_e32 v116, v103, v103
	v_mul_f32_e32 v118, v98, v98
	v_mul_f32_e32 v119, v99, v99
	v_pk_fma_f32 v[114:115], v[100:101], v[100:101], v[114:115] op_sel_hi:[1,1,0]
	v_pk_fma_f32 v[116:117], v[102:103], v[102:103], v[116:117] op_sel_hi:[1,1,0]
	v_mov_b32_e32 v115, v118
	v_mov_b32_e32 v117, v119
	v_pk_add_f32 v[114:115], v[114:115], v[116:117]
	s_nop 0
	v_pk_add_f32 v[112:113], v[112:113], v[114:115]
	s_nop 0
	v_add_f32_e32 v112, v112, v113
	ds_bpermute_b32 v113, v173, v112
	s_waitcnt lgkmcnt(0)
	v_add_f32_e32 v112, v112, v113
	ds_bpermute_b32 v113, v174, v112
	s_waitcnt lgkmcnt(0)
	v_add_f32_e32 v112, v112, v113
	v_fmamk_f32 v112, v112, 0x3c800000, v178
	v_mul_f32_e32 v113, 0x4b800000, v112
	v_cmp_gt_f32_e32 vcc, s81, v112
	s_nop 1
	v_cndmask_b32_e32 v112, v112, v113, vcc
	v_rsq_f32_e32 v112, v112
	s_nop 0
	v_mul_f32_e32 v113, 0x45800000, v112
	v_cndmask_b32_e32 v168, v112, v113, vcc
; __device__ __forceinline__ u32x4 pack8(const f32x4& a, const f32x4& b) { u32x4 w; w.x = pk2(a[0], a[1]); w.y = pk2(a[2], a[3]); w.z = pk2(b[0], b[1]); w.w = pk2(b[2], b[3]); return w; }
;     __device__ __forceinline__ void operator()(const AccT& acc, const Unit& u, int wr, int wc, int fr, int fq) const {
;     ...
;             for (int m = 0; m < 4; ++m) {
;                 const int row = row0 + ai * 128 + m * 16; float rs = 1.f;
;                 if (kind < 2) { float ss = 0.f;
; #pragma unroll
;                     for (int bj = 0; bj < 2; ++bj)
; #pragma unroll
;                         for (int n = 0; n < 2; ++n) { const f32x4 v = acc[ai][bj][m][n]; ss += (v[0] * v[0] + v[1] * v[1]) + (v[2] * v[2] + v[3] * v[3]); }
;                     ss += __shfl_xor(ss, 16); ss += __shfl_xor(ss, 32); rs = rsqrtf(ss * (1.f / 64.f) + EPS); }
;                 bf16_t* rp = base + (size_t)row * BR + tile * 256 + 64 * wc + 8 * fq;
; #pragma unroll
;                 for (int bj = 0; bj < 2; ++bj) { const f32x4 v0 = acc[ai][bj][m][0] * rs * gv[bj][0], v1 = acc[ai][bj][m][1] * rs * gv[bj][1];
;                     __builtin_nontemporal_store(pack8(v0, v1), (u32x4*)(rp + 32 * bj)); }
.LBB0_131:
	s_nop 0
	v_or_b32_e32 v112, 16, v164
	v_ashrrev_i32_e32 v113, 31, v112
	v_lshlrev_b64 v[112:113], 12, v[112:113]
	v_pk_mul_f32 v[110:111], v[110:111], v[168:169] op_sel_hi:[1,0]
	v_pk_mul_f32 v[108:109], v[108:109], v[168:169] op_sel_hi:[1,0]
	v_pk_mul_f32 v[106:107], v[106:107], v[168:169] op_sel_hi:[1,0]
	v_pk_mul_f32 v[104:105], v[104:105], v[168:169] op_sel_hi:[1,0]
	v_lshl_add_u64 v[112:113], v[166:167], 0, v[112:113]
	v_pk_mul_f32 v[110:111], v[152:153], v[110:111]
	v_pk_mul_f32 v[108:109], v[150:151], v[108:109]
	v_pk_mul_f32 v[114:115], v[156:157], v[106:107]
	v_pk_mul_f32 v[106:107], v[148:149], v[104:105]
	v_cvt_pk_bf16_f32 v104, v108, v109
	v_cvt_pk_bf16_f32 v105, v110, v111
	v_pk_mul_f32 v[98:99], v[98:99], v[168:169] op_sel_hi:[1,0]
	v_pk_mul_f32 v[96:97], v[96:97], v[168:169] op_sel_hi:[1,0]
	v_cvt_pk_bf16_f32 v106, v106, v107
	v_cvt_pk_bf16_f32 v107, v114, v115
	v_mov_b32_e32 v240, v104
	v_mov_b32_e32 v241, v105
	v_mov_b32_e32 v242, v106
	v_mov_b32_e32 v243, v107
	v_pk_mul_f32 v[102:103], v[102:103], v[168:169] op_sel_hi:[1,0]
	v_pk_mul_f32 v[100:101], v[100:101], v[168:169] op_sel_hi:[1,0]
	v_pk_mul_f32 v[104:105], v[162:163], v[98:99]
	v_pk_mul_f32 v[98:99], v[154:155], v[96:97]
	v_pk_mul_f32 v[102:103], v[160:161], v[102:103]
	v_pk_mul_f32 v[100:101], v[158:159], v[100:101]
	s_and_b64 vcc, exec, s[6:7]
	v_cvt_pk_bf16_f32 v96, v100, v101
	v_cvt_pk_bf16_f32 v97, v102, v103
	v_cvt_pk_bf16_f32 v98, v98, v99
	v_cvt_pk_bf16_f32 v99, v104, v105
	v_mov_b32_e32 v244, v96
	v_mov_b32_e32 v245, v97
	v_mov_b32_e32 v246, v98
	v_mov_b32_e32 v247, v99
	v_mov_b32_dpp v244, v240 row_shl:8 row_mask:0xf bank_mask:0x3
	v_mov_b32_dpp v245, v241 row_shl:8 row_mask:0xf bank_mask:0x3
	v_mov_b32_dpp v246, v242 row_shl:8 row_mask:0xf bank_mask:0x3
	v_mov_b32_dpp v247, v243 row_shl:8 row_mask:0xf bank_mask:0x3
	v_mov_b32_dpp v240, v96 row_shr:8 row_mask:0xf bank_mask:0xc
	v_mov_b32_dpp v241, v97 row_shr:8 row_mask:0xf bank_mask:0xc
	v_mov_b32_dpp v242, v98 row_shr:8 row_mask:0xf bank_mask:0xc
	v_mov_b32_dpp v243, v99 row_shr:8 row_mask:0xf bank_mask:0xc
	v_lshl_add_u64 v[252:253], v[112:113], 0, v[248:249]
	v_lshl_add_u64 v[254:255], v[112:113], 0, v[250:251]
	global_store_dwordx4 v[252:253], v[240:243], off nt
	global_store_dwordx4 v[254:255], v[244:247], off nt
	s_nop 1
	v_mov_b32_e32 v96, 1.0
	v_mov_b32_e32 v98, 1.0
	s_cbranch_vccnz .LBB0_133
	v_pk_mul_f32 v[98:99], v[94:95], v[94:95]
	v_pk_mul_f32 v[100:101], v[92:93], v[92:93]
	v_mul_f32_e32 v97, v80, v80
	v_pk_mov_b32 v[102:103], v[100:101], v[98:99] op_sel:[1,0]
	v_mov_b32_e32 v101, v99
	v_pk_add_f32 v[98:99], v[102:103], v[100:101]
	v_pk_mul_f32 v[100:101], v[90:91], v[90:91]
	v_pk_mul_f32 v[102:103], v[88:89], v[88:89]
	v_pk_add_f32 v[98:99], v[98:99], v[98:99] op_sel:[0,1] op_sel_hi:[1,0]
	v_pk_mov_b32 v[104:105], v[102:103], v[100:101] op_sel:[1,0]
	v_mov_b32_e32 v103, v101
	v_pk_add_f32 v[100:101], v[104:105], v[102:103]
	v_mul_f32_e32 v102, v81, v81
	v_pk_add_f32 v[100:101], v[100:101], v[100:101] op_sel:[0,1] op_sel_hi:[1,0]
	v_mov_b32_e32 v99, v97
	v_mov_b32_e32 v101, v102
	v_pk_add_f32 v[98:99], v[98:99], v[100:101]
	v_mul_f32_e32 v100, v85, v85
	v_mul_f32_e32 v103, v82, v82
	v_pk_fma_f32 v[100:101], v[84:85], v[84:85], v[100:101] op_sel_hi:[1,1,0]
	v_mul_f32_e32 v102, v87, v87
	v_mul_f32_e32 v104, v83, v83
	v_mov_b32_e32 v101, v103
	v_pk_fma_f32 v[102:103], v[86:87], v[86:87], v[102:103] op_sel_hi:[1,1,0]
	s_nop 0
	v_mov_b32_e32 v103, v104
	v_pk_add_f32 v[100:101], v[100:101], v[102:103]
	s_nop 0
	v_pk_add_f32 v[98:99], v[98:99], v[100:101]
	s_nop 0
	v_add_f32_e32 v97, v98, v99
	ds_bpermute_b32 v98, v173, v97
	s_waitcnt lgkmcnt(0)
	v_add_f32_e32 v97, v97, v98
	ds_bpermute_b32 v98, v174, v97
	s_waitcnt lgkmcnt(0)
	v_add_f32_e32 v97, v97, v98
	v_fmamk_f32 v97, v97, 0x3c800000, v178
	v_mul_f32_e32 v98, 0x4b800000, v97
	v_cmp_gt_f32_e32 vcc, s81, v97
	s_nop 1
	v_cndmask_b32_e32 v97, v97, v98, vcc
	v_rsq_f32_e32 v97, v97
	s_nop 0
	v_mul_f32_e32 v98, 0x45800000, v97
	v_cndmask_b32_e32 v98, v97, v98, vcc
.LBB0_133:
	v_or_b32_e32 v100, 32, v164
	v_ashrrev_i32_e32 v101, 31, v100
	v_lshlrev_b64 v[100:101], 12, v[100:101]
	v_pk_mul_f32 v[94:95], v[94:95], v[98:99] op_sel_hi:[1,0]
	v_pk_mul_f32 v[92:93], v[92:93], v[98:99] op_sel_hi:[1,0]
	v_pk_mul_f32 v[90:91], v[90:91], v[98:99] op_sel_hi:[1,0]
	v_pk_mul_f32 v[88:89], v[88:89], v[98:99] op_sel_hi:[1,0]
	v_lshl_add_u64 v[100:101], v[166:167], 0, v[100:101]
	v_pk_mul_f32 v[94:95], v[152:153], v[94:95]
	v_pk_mul_f32 v[92:93], v[150:151], v[92:93]
	v_pk_mul_f32 v[102:103], v[156:157], v[90:91]
	v_pk_mul_f32 v[90:91], v[148:149], v[88:89]
	v_cvt_pk_bf16_f32 v88, v92, v93
	v_cvt_pk_bf16_f32 v89, v94, v95
	v_pk_mul_f32 v[82:83], v[82:83], v[98:99] op_sel_hi:[1,0]
	v_pk_mul_f32 v[80:81], v[80:81], v[98:99] op_sel_hi:[1,0]
	v_cvt_pk_bf16_f32 v90, v90, v91
	v_cvt_pk_bf16_f32 v91, v102, v103
	v_mov_b32_e32 v240, v88
	v_mov_b32_e32 v241, v89
	v_mov_b32_e32 v242, v90
	v_mov_b32_e32 v243, v91
	v_pk_mul_f32 v[86:87], v[86:87], v[98:99] op_sel_hi:[1,0]
	v_pk_mul_f32 v[84:85], v[84:85], v[98:99] op_sel_hi:[1,0]
	v_pk_mul_f32 v[88:89], v[162:163], v[82:83]
	v_pk_mul_f32 v[82:83], v[154:155], v[80:81]
	s_and_b64 vcc, exec, s[6:7]
	v_pk_mul_f32 v[86:87], v[160:161], v[86:87]
	v_pk_mul_f32 v[84:85], v[158:159], v[84:85]
	s_nop 0
	v_cvt_pk_bf16_f32 v80, v84, v85
	v_cvt_pk_bf16_f32 v81, v86, v87
	v_cvt_pk_bf16_f32 v82, v82, v83
	v_cvt_pk_bf16_f32 v83, v88, v89
	v_mov_b32_e32 v244, v80
	v_mov_b32_e32 v245, v81
	v_mov_b32_e32 v246, v82
	v_mov_b32_e32 v247, v83
	v_mov_b32_dpp v244, v240 row_shl:8 row_mask:0xf bank_mask:0x3
	v_mov_b32_dpp v245, v241 row_shl:8 row_mask:0xf bank_mask:0x3
	v_mov_b32_dpp v246, v242 row_shl:8 row_mask:0xf bank_mask:0x3
	v_mov_b32_dpp v247, v243 row_shl:8 row_mask:0xf bank_mask:0x3
	v_mov_b32_dpp v240, v80 row_shr:8 row_mask:0xf bank_mask:0xc
	v_mov_b32_dpp v241, v81 row_shr:8 row_mask:0xf bank_mask:0xc
	v_mov_b32_dpp v242, v82 row_shr:8 row_mask:0xf bank_mask:0xc
	v_mov_b32_dpp v243, v83 row_shr:8 row_mask:0xf bank_mask:0xc
	v_lshl_add_u64 v[252:253], v[100:101], 0, v[248:249]
	v_lshl_add_u64 v[254:255], v[100:101], 0, v[250:251]
	global_store_dwordx4 v[252:253], v[240:243], off nt
	global_store_dwordx4 v[254:255], v[244:247], off nt
	s_cbranch_vccnz .LBB0_135
; __device__ __forceinline__ u32x4 pack8(const f32x4& a, const f32x4& b) { u32x4 w; w.x = pk2(a[0], a[1]); w.y = pk2(a[2], a[3]); w.z = pk2(b[0], b[1]); w.w = pk2(b[2], b[3]); return w; }
;     __device__ __forceinline__ void operator()(const AccT& acc, const Unit& u, int wr, int wc, int fr, int fq) const {
;     ...
;             for (int m = 0; m < 4; ++m) {
;                 const int row = row0 + ai * 128 + m * 16; float rs = 1.f;
;                 if (kind < 2) { float ss = 0.f;
; #pragma unroll
;                     for (int bj = 0; bj < 2; ++bj)
; #pragma unroll
;                         for (int n = 0; n < 2; ++n) { const f32x4 v = acc[ai][bj][m][n]; ss += (v[0] * v[0] + v[1] * v[1]) + (v[2] * v[2] + v[3] * v[3]); }
;                     ss += __shfl_xor(ss, 16); ss += __shfl_xor(ss, 32); rs = rsqrtf(ss * (1.f / 64.f) + EPS); }
;                 bf16_t* rp = base + (size_t)row * BR + tile * 256 + 64 * wc + 8 * fq;
; #pragma unroll
;                 for (int bj = 0; bj < 2; ++bj) { const f32x4 v0 = acc[ai][bj][m][0] * rs * gv[bj][0], v1 = acc[ai][bj][m][1] * rs * gv[bj][1];
;                     __builtin_nontemporal_store(pack8(v0, v1), (u32x4*)(rp + 32 * bj)); }
	s_nop 0
	v_pk_mul_f32 v[80:81], v[78:79], v[78:79]
	v_pk_mul_f32 v[82:83], v[76:77], v[76:77]
	s_nop 0
	v_pk_mov_b32 v[84:85], v[82:83], v[80:81] op_sel:[1,0]
	v_mov_b32_e32 v83, v81
	v_pk_add_f32 v[80:81], v[84:85], v[82:83]
	v_pk_mul_f32 v[82:83], v[74:75], v[74:75]
	v_pk_mul_f32 v[84:85], v[72:73], v[72:73]
	v_pk_add_f32 v[80:81], v[80:81], v[80:81] op_sel:[0,1] op_sel_hi:[1,0]
	v_pk_mov_b32 v[86:87], v[84:85], v[82:83] op_sel:[1,0]
	v_mov_b32_e32 v85, v83
	v_pk_add_f32 v[82:83], v[86:87], v[84:85]
	v_mul_f32_e32 v84, v64, v64
	v_mul_f32_e32 v85, v65, v65
	v_pk_add_f32 v[82:83], v[82:83], v[82:83] op_sel:[0,1] op_sel_hi:[1,0]
	v_mov_b32_e32 v81, v84
	v_mov_b32_e32 v83, v85
	v_pk_add_f32 v[80:81], v[80:81], v[82:83]
	v_mul_f32_e32 v82, v69, v69
	v_mul_f32_e32 v84, v71, v71
	v_mul_f32_e32 v86, v66, v66
	v_mul_f32_e32 v87, v67, v67
	v_pk_fma_f32 v[82:83], v[68:69], v[68:69], v[82:83] op_sel_hi:[1,1,0]
	v_pk_fma_f32 v[84:85], v[70:71], v[70:71], v[84:85] op_sel_hi:[1,1,0]
	v_mov_b32_e32 v83, v86
	v_mov_b32_e32 v85, v87
	v_pk_add_f32 v[82:83], v[82:83], v[84:85]
	s_nop 0
	v_pk_add_f32 v[80:81], v[80:81], v[82:83]
	s_nop 0
	v_add_f32_e32 v80, v80, v81
	ds_bpermute_b32 v81, v173, v80
	s_waitcnt lgkmcnt(0)
	v_add_f32_e32 v80, v80, v81
	ds_bpermute_b32 v81, v174, v80
	s_waitcnt lgkmcnt(0)
	v_add_f32_e32 v80, v80, v81
	v_fmamk_f32 v80, v80, 0x3c800000, v178
	v_mul_f32_e32 v81, 0x4b800000, v80
	v_cmp_gt_f32_e32 vcc, s81, v80
	s_nop 1
	v_cndmask_b32_e32 v80, v80, v81, vcc
	v_rsq_f32_e32 v80, v80
	s_nop 0
	v_mul_f32_e32 v81, 0x45800000, v80
	v_cndmask_b32_e32 v96, v80, v81, vcc
.LBB0_135:
	s_nop 0
	v_or_b32_e32 v80, 48, v164
	v_ashrrev_i32_e32 v81, 31, v80
	v_lshlrev_b64 v[80:81], 12, v[80:81]
	v_pk_mul_f32 v[78:79], v[78:79], v[96:97] op_sel_hi:[1,0]
	v_pk_mul_f32 v[76:77], v[76:77], v[96:97] op_sel_hi:[1,0]
	v_pk_mul_f32 v[74:75], v[74:75], v[96:97] op_sel_hi:[1,0]
	v_pk_mul_f32 v[72:73], v[72:73], v[96:97] op_sel_hi:[1,0]
	v_lshl_add_u64 v[80:81], v[166:167], 0, v[80:81]
	v_pk_mul_f32 v[78:79], v[152:153], v[78:79]
	v_pk_mul_f32 v[76:77], v[150:151], v[76:77]
	v_pk_mul_f32 v[82:83], v[156:157], v[74:75]
	v_pk_mul_f32 v[74:75], v[148:149], v[72:73]
	v_cvt_pk_bf16_f32 v72, v76, v77
	v_cvt_pk_bf16_f32 v73, v78, v79
	v_pk_mul_f32 v[68:69], v[68:69], v[96:97] op_sel_hi:[1,0]
	v_pk_mul_f32 v[66:67], v[66:67], v[96:97] op_sel_hi:[1,0]
	v_pk_mul_f32 v[64:65], v[64:65], v[96:97] op_sel_hi:[1,0]
	v_cvt_pk_bf16_f32 v74, v74, v75
	v_cvt_pk_bf16_f32 v75, v82, v83
	v_mov_b32_e32 v240, v72
	v_mov_b32_e32 v241, v73
	v_mov_b32_e32 v242, v74
	v_mov_b32_e32 v243, v75
	v_pk_mul_f32 v[70:71], v[70:71], v[96:97] op_sel_hi:[1,0]
	v_pk_mul_f32 v[68:69], v[158:159], v[68:69]
	v_pk_mul_f32 v[72:73], v[162:163], v[66:67]
	v_pk_mul_f32 v[66:67], v[154:155], v[64:65]
	v_cvt_pk_bf16_f32 v64, v68, v69
	v_pk_mul_f32 v[70:71], v[160:161], v[70:71]
	s_and_b64 vcc, exec, s[6:7]
	v_cvt_pk_bf16_f32 v65, v70, v71
	v_cvt_pk_bf16_f32 v66, v66, v67
	v_cvt_pk_bf16_f32 v67, v72, v73
	v_mov_b32_e32 v244, v64
	v_mov_b32_e32 v245, v65
	v_mov_b32_e32 v246, v66
	v_mov_b32_e32 v247, v67
	v_mov_b32_dpp v244, v240 row_shl:8 row_mask:0xf bank_mask:0x3
	v_mov_b32_dpp v245, v241 row_shl:8 row_mask:0xf bank_mask:0x3
	v_mov_b32_dpp v246, v242 row_shl:8 row_mask:0xf bank_mask:0x3
	v_mov_b32_dpp v247, v243 row_shl:8 row_mask:0xf bank_mask:0x3
	v_mov_b32_dpp v240, v64 row_shr:8 row_mask:0xf bank_mask:0xc
	v_mov_b32_dpp v241, v65 row_shr:8 row_mask:0xf bank_mask:0xc
	v_mov_b32_dpp v242, v66 row_shr:8 row_mask:0xf bank_mask:0xc
	v_mov_b32_dpp v243, v67 row_shr:8 row_mask:0xf bank_mask:0xc
	v_lshl_add_u64 v[252:253], v[80:81], 0, v[248:249]
	v_lshl_add_u64 v[254:255], v[80:81], 0, v[250:251]
	global_store_dwordx4 v[252:253], v[240:243], off nt
	global_store_dwordx4 v[254:255], v[244:247], off nt
	v_mov_b32_e32 v68, 1.0
	s_nop 0
	v_mov_b32_e32 v64, 1.0
	s_cbranch_vccnz .LBB0_137
	v_pk_mul_f32 v[66:67], v[62:63], v[62:63]
	v_pk_mul_f32 v[68:69], v[60:61], v[60:61]
	v_mul_f32_e32 v65, v48, v48
	v_pk_mov_b32 v[70:71], v[68:69], v[66:67] op_sel:[1,0]
	v_mov_b32_e32 v69, v67
	v_pk_add_f32 v[66:67], v[70:71], v[68:69]
	v_pk_mul_f32 v[68:69], v[58:59], v[58:59]
	v_pk_mul_f32 v[70:71], v[56:57], v[56:57]
	v_pk_add_f32 v[66:67], v[66:67], v[66:67] op_sel:[0,1] op_sel_hi:[1,0]
	v_pk_mov_b32 v[72:73], v[70:71], v[68:69] op_sel:[1,0]
	v_mov_b32_e32 v71, v69
	v_pk_add_f32 v[68:69], v[72:73], v[70:71]
	v_mul_f32_e32 v70, v49, v49
	v_pk_add_f32 v[68:69], v[68:69], v[68:69] op_sel:[0,1] op_sel_hi:[1,0]
	v_mov_b32_e32 v67, v65
	v_mov_b32_e32 v69, v70
	v_pk_add_f32 v[66:67], v[66:67], v[68:69]
	v_mul_f32_e32 v68, v53, v53
	v_mul_f32_e32 v71, v50, v50
	v_pk_fma_f32 v[68:69], v[52:53], v[52:53], v[68:69] op_sel_hi:[1,1,0]
	v_mul_f32_e32 v70, v55, v55
	v_mul_f32_e32 v72, v51, v51
	v_mov_b32_e32 v69, v71
	v_pk_fma_f32 v[70:71], v[54:55], v[54:55], v[70:71] op_sel_hi:[1,1,0]
	s_nop 0
	v_mov_b32_e32 v71, v72
	v_pk_add_f32 v[68:69], v[68:69], v[70:71]
	s_nop 0
	v_pk_add_f32 v[66:67], v[66:67], v[68:69]
	s_nop 0
	v_add_f32_e32 v65, v66, v67
	ds_bpermute_b32 v66, v173, v65
	s_waitcnt lgkmcnt(0)
	v_add_f32_e32 v65, v65, v66
	ds_bpermute_b32 v66, v174, v65
	s_waitcnt lgkmcnt(0)
	v_add_f32_e32 v65, v65, v66
	v_fmamk_f32 v65, v65, 0x3c800000, v178
	v_mul_f32_e32 v66, 0x4b800000, v65
	v_cmp_gt_f32_e32 vcc, s81, v65
	s_nop 1
	v_cndmask_b32_e32 v65, v65, v66, vcc
	v_rsq_f32_e32 v65, v65
	s_nop 0
	v_mul_f32_e32 v66, 0x45800000, v65
	v_cndmask_b32_e32 v68, v65, v66, vcc
; __device__ __forceinline__ u32x4 pack8(const f32x4& a, const f32x4& b) { u32x4 w; w.x = pk2(a[0], a[1]); w.y = pk2(a[2], a[3]); w.z = pk2(b[0], b[1]); w.w = pk2(b[2], b[3]); return w; }
;     __device__ __forceinline__ void operator()(const AccT& acc, const Unit& u, int wr, int wc, int fr, int fq) const {
;     ...
;             for (int m = 0; m < 4; ++m) {
;                 const int row = row0 + ai * 128 + m * 16; float rs = 1.f;
;                 if (kind < 2) { float ss = 0.f;
; #pragma unroll
;                     for (int bj = 0; bj < 2; ++bj)
; #pragma unroll
;                         for (int n = 0; n < 2; ++n) { const f32x4 v = acc[ai][bj][m][n]; ss += (v[0] * v[0] + v[1] * v[1]) + (v[2] * v[2] + v[3] * v[3]); }
;                     ss += __shfl_xor(ss, 16); ss += __shfl_xor(ss, 32); rs = rsqrtf(ss * (1.f / 64.f) + EPS); }
;                 bf16_t* rp = base + (size_t)row * BR + tile * 256 + 64 * wc + 8 * fq;
; #pragma unroll
;                 for (int bj = 0; bj < 2; ++bj) { const f32x4 v0 = acc[ai][bj][m][0] * rs * gv[bj][0], v1 = acc[ai][bj][m][1] * rs * gv[bj][1];
;                     __builtin_nontemporal_store(pack8(v0, v1), (u32x4*)(rp + 32 * bj)); }
.LBB0_137:
	v_lshlrev_b64 v[66:67], 12, v[164:165]
	v_pk_mul_f32 v[60:61], v[60:61], v[68:69] op_sel_hi:[1,0]
	v_lshl_add_u64 v[66:67], v[166:167], 0, v[66:67]
	v_pk_mul_f32 v[60:61], v[150:151], v[60:61]
	v_pk_mul_f32 v[58:59], v[58:59], v[68:69] op_sel_hi:[1,0]
	v_pk_mul_f32 v[56:57], v[56:57], v[68:69] op_sel_hi:[1,0]
	v_pk_mul_f32 v[62:63], v[62:63], v[68:69] op_sel_hi:[1,0]
	v_pk_mul_f32 v[72:73], v[156:157], v[58:59]
	v_pk_mul_f32 v[58:59], v[148:149], v[56:57]
	v_cvt_pk_bf16_f32 v56, v60, v61
	v_add_co_u32_e32 v60, vcc, s83, v66
	v_pk_mul_f32 v[62:63], v[152:153], v[62:63]
	s_nop 0
	v_addc_co_u32_e32 v61, vcc, 0, v67, vcc
	v_cvt_pk_bf16_f32 v57, v62, v63
	v_pk_mul_f32 v[50:51], v[50:51], v[68:69] op_sel_hi:[1,0]
	v_pk_mul_f32 v[48:49], v[48:49], v[68:69] op_sel_hi:[1,0]
	v_lshl_add_u64 v[70:71], v[66:67], 0, s[24:25]
	v_cvt_pk_bf16_f32 v58, v58, v59
	v_cvt_pk_bf16_f32 v59, v72, v73
	v_mov_b32_e32 v240, v56
	v_mov_b32_e32 v241, v57
	v_mov_b32_e32 v242, v58
	v_mov_b32_e32 v243, v59
	v_pk_mul_f32 v[54:55], v[54:55], v[68:69] op_sel_hi:[1,0]
	v_pk_mul_f32 v[52:53], v[52:53], v[68:69] op_sel_hi:[1,0]
	v_pk_mul_f32 v[56:57], v[162:163], v[50:51]
	v_pk_mul_f32 v[50:51], v[154:155], v[48:49]
	s_and_b64 vcc, exec, s[6:7]
	v_pk_mul_f32 v[54:55], v[160:161], v[54:55]
	v_pk_mul_f32 v[52:53], v[158:159], v[52:53]
	s_nop 0
	v_cvt_pk_bf16_f32 v48, v52, v53
	v_cvt_pk_bf16_f32 v49, v54, v55
	v_cvt_pk_bf16_f32 v50, v50, v51
	v_cvt_pk_bf16_f32 v51, v56, v57
	v_mov_b32_e32 v244, v48
	v_mov_b32_e32 v245, v49
	v_mov_b32_e32 v246, v50
	v_mov_b32_e32 v247, v51
	v_mov_b32_dpp v244, v240 row_shl:8 row_mask:0xf bank_mask:0x3
	v_mov_b32_dpp v245, v241 row_shl:8 row_mask:0xf bank_mask:0x3
	v_mov_b32_dpp v246, v242 row_shl:8 row_mask:0xf bank_mask:0x3
	v_mov_b32_dpp v247, v243 row_shl:8 row_mask:0xf bank_mask:0x3
	v_mov_b32_dpp v240, v48 row_shr:8 row_mask:0xf bank_mask:0xc
	v_mov_b32_dpp v241, v49 row_shr:8 row_mask:0xf bank_mask:0xc
	v_mov_b32_dpp v242, v50 row_shr:8 row_mask:0xf bank_mask:0xc
	v_mov_b32_dpp v243, v51 row_shr:8 row_mask:0xf bank_mask:0xc
	v_lshl_add_u64 v[252:253], v[60:61], 0, v[248:249]
	v_lshl_add_u64 v[254:255], v[60:61], 0, v[250:251]
	global_store_dwordx4 v[252:253], v[240:243], off nt
	global_store_dwordx4 v[254:255], v[244:247], off nt
	s_cbranch_vccnz .LBB0_139
	s_nop 0
	v_pk_mul_f32 v[48:49], v[46:47], v[46:47]
	v_pk_mul_f32 v[50:51], v[44:45], v[44:45]
	s_nop 0
	v_pk_mov_b32 v[52:53], v[50:51], v[48:49] op_sel:[1,0]
	v_mov_b32_e32 v51, v49
	v_pk_add_f32 v[48:49], v[52:53], v[50:51]
	v_pk_mul_f32 v[50:51], v[42:43], v[42:43]
	v_pk_mul_f32 v[52:53], v[40:41], v[40:41]
	v_pk_add_f32 v[48:49], v[48:49], v[48:49] op_sel:[0,1] op_sel_hi:[1,0]
	v_pk_mov_b32 v[54:55], v[52:53], v[50:51] op_sel:[1,0]
	v_mov_b32_e32 v53, v51
	v_pk_add_f32 v[50:51], v[54:55], v[52:53]
	v_mul_f32_e32 v52, v32, v32
	v_mul_f32_e32 v53, v33, v33
	v_pk_add_f32 v[50:51], v[50:51], v[50:51] op_sel:[0,1] op_sel_hi:[1,0]
	v_mov_b32_e32 v49, v52
	v_mov_b32_e32 v51, v53
	v_pk_add_f32 v[48:49], v[48:49], v[50:51]
	v_mul_f32_e32 v50, v37, v37
	v_mul_f32_e32 v52, v39, v39
	v_mul_f32_e32 v54, v34, v34
	v_mul_f32_e32 v55, v35, v35
	v_pk_fma_f32 v[50:51], v[36:37], v[36:37], v[50:51] op_sel_hi:[1,1,0]
	v_pk_fma_f32 v[52:53], v[38:39], v[38:39], v[52:53] op_sel_hi:[1,1,0]
	v_mov_b32_e32 v51, v54
	v_mov_b32_e32 v53, v55
	v_pk_add_f32 v[50:51], v[50:51], v[52:53]
	s_nop 0
	v_pk_add_f32 v[48:49], v[48:49], v[50:51]
	s_nop 0
	v_add_f32_e32 v48, v48, v49
	ds_bpermute_b32 v49, v173, v48
	s_waitcnt lgkmcnt(0)
	v_add_f32_e32 v48, v48, v49
	ds_bpermute_b32 v49, v174, v48
	s_waitcnt lgkmcnt(0)
	v_add_f32_e32 v48, v48, v49
	v_fmamk_f32 v48, v48, 0x3c800000, v178
	v_mul_f32_e32 v49, 0x4b800000, v48
	v_cmp_gt_f32_e32 vcc, s81, v48
	s_nop 1
	v_cndmask_b32_e32 v48, v48, v49, vcc
	v_rsq_f32_e32 v48, v48
	s_nop 0
	v_mul_f32_e32 v49, 0x45800000, v48
	v_cndmask_b32_e32 v64, v48, v49, vcc
.LBB0_139:
	v_pk_mul_f32 v[44:45], v[44:45], v[64:65] op_sel_hi:[1,0]
	v_pk_mul_f32 v[42:43], v[42:43], v[64:65] op_sel_hi:[1,0]
	v_pk_mul_f32 v[44:45], v[150:151], v[44:45]
	v_pk_mul_f32 v[40:41], v[40:41], v[64:65] op_sel_hi:[1,0]
	v_pk_mul_f32 v[46:47], v[46:47], v[64:65] op_sel_hi:[1,0]
	v_pk_mul_f32 v[50:51], v[156:157], v[42:43]
	v_pk_mul_f32 v[42:43], v[148:149], v[40:41]
	v_cvt_pk_bf16_f32 v40, v44, v45
	v_add_co_u32_e32 v44, vcc, s84, v66
	v_pk_mul_f32 v[46:47], v[152:153], v[46:47]
	s_nop 0
	v_addc_co_u32_e32 v45, vcc, 0, v67, vcc
	v_cvt_pk_bf16_f32 v41, v46, v47
	v_pk_mul_f32 v[36:37], v[36:37], v[64:65] op_sel_hi:[1,0]
	v_pk_mul_f32 v[34:35], v[34:35], v[64:65] op_sel_hi:[1,0]
	v_pk_mul_f32 v[32:33], v[32:33], v[64:65] op_sel_hi:[1,0]
	v_lshl_add_u64 v[48:49], v[66:67], 0, s[36:37]
	v_cvt_pk_bf16_f32 v42, v42, v43
	v_cvt_pk_bf16_f32 v43, v50, v51
	v_mov_b32_e32 v240, v40
	v_mov_b32_e32 v241, v41
	v_mov_b32_e32 v242, v42
	v_mov_b32_e32 v243, v43
	v_pk_mul_f32 v[38:39], v[38:39], v[64:65] op_sel_hi:[1,0]
	v_pk_mul_f32 v[36:37], v[158:159], v[36:37]
	v_pk_mul_f32 v[40:41], v[162:163], v[34:35]
	v_pk_mul_f32 v[34:35], v[154:155], v[32:33]
	v_cvt_pk_bf16_f32 v32, v36, v37
	v_pk_mul_f32 v[38:39], v[160:161], v[38:39]
	s_and_b64 vcc, exec, s[6:7]
	v_cvt_pk_bf16_f32 v33, v38, v39
	v_cvt_pk_bf16_f32 v34, v34, v35
	v_cvt_pk_bf16_f32 v35, v40, v41
	v_mov_b32_e32 v244, v32
	v_mov_b32_e32 v245, v33
	v_mov_b32_e32 v246, v34
	v_mov_b32_e32 v247, v35
	v_mov_b32_dpp v244, v240 row_shl:8 row_mask:0xf bank_mask:0x3
	v_mov_b32_dpp v245, v241 row_shl:8 row_mask:0xf bank_mask:0x3
	v_mov_b32_dpp v246, v242 row_shl:8 row_mask:0xf bank_mask:0x3
	v_mov_b32_dpp v247, v243 row_shl:8 row_mask:0xf bank_mask:0x3
	v_mov_b32_dpp v240, v32 row_shr:8 row_mask:0xf bank_mask:0xc
	v_mov_b32_dpp v241, v33 row_shr:8 row_mask:0xf bank_mask:0xc
	v_mov_b32_dpp v242, v34 row_shr:8 row_mask:0xf bank_mask:0xc
	v_mov_b32_dpp v243, v35 row_shr:8 row_mask:0xf bank_mask:0xc
	v_lshl_add_u64 v[252:253], v[44:45], 0, v[248:249]
	v_lshl_add_u64 v[254:255], v[44:45], 0, v[250:251]
	global_store_dwordx4 v[252:253], v[240:243], off nt
	global_store_dwordx4 v[254:255], v[244:247], off nt
	v_mov_b32_e32 v36, 1.0
	s_nop 0
	v_mov_b32_e32 v32, 1.0
	s_cbranch_vccnz .LBB0_141
; __device__ __forceinline__ u32x4 pack8(const f32x4& a, const f32x4& b) { u32x4 w; w.x = pk2(a[0], a[1]); w.y = pk2(a[2], a[3]); w.z = pk2(b[0], b[1]); w.w = pk2(b[2], b[3]); return w; }
;     __device__ __forceinline__ void operator()(const AccT& acc, const Unit& u, int wr, int wc, int fr, int fq) const {
;     ...
;             for (int m = 0; m < 4; ++m) {
;                 const int row = row0 + ai * 128 + m * 16; float rs = 1.f;
;                 if (kind < 2) { float ss = 0.f;
; #pragma unroll
;                     for (int bj = 0; bj < 2; ++bj)
; #pragma unroll
;                         for (int n = 0; n < 2; ++n) { const f32x4 v = acc[ai][bj][m][n]; ss += (v[0] * v[0] + v[1] * v[1]) + (v[2] * v[2] + v[3] * v[3]); }
;                     ss += __shfl_xor(ss, 16); ss += __shfl_xor(ss, 32); rs = rsqrtf(ss * (1.f / 64.f) + EPS); }
;                 bf16_t* rp = base + (size_t)row * BR + tile * 256 + 64 * wc + 8 * fq;
; #pragma unroll
;                 for (int bj = 0; bj < 2; ++bj) { const f32x4 v0 = acc[ai][bj][m][0] * rs * gv[bj][0], v1 = acc[ai][bj][m][1] * rs * gv[bj][1];
;                     __builtin_nontemporal_store(pack8(v0, v1), (u32x4*)(rp + 32 * bj)); }
	v_pk_mul_f32 v[34:35], v[30:31], v[30:31]
	v_pk_mul_f32 v[36:37], v[28:29], v[28:29]
	v_mul_f32_e32 v33, v16, v16
	v_pk_mov_b32 v[38:39], v[36:37], v[34:35] op_sel:[1,0]
	v_mov_b32_e32 v37, v35
	v_pk_add_f32 v[34:35], v[38:39], v[36:37]
	v_pk_mul_f32 v[36:37], v[26:27], v[26:27]
	v_pk_mul_f32 v[38:39], v[24:25], v[24:25]
	v_pk_add_f32 v[34:35], v[34:35], v[34:35] op_sel:[0,1] op_sel_hi:[1,0]
	v_pk_mov_b32 v[40:41], v[38:39], v[36:37] op_sel:[1,0]
	v_mov_b32_e32 v39, v37
	v_pk_add_f32 v[36:37], v[40:41], v[38:39]
	v_mul_f32_e32 v38, v17, v17
	v_pk_add_f32 v[36:37], v[36:37], v[36:37] op_sel:[0,1] op_sel_hi:[1,0]
	v_mov_b32_e32 v35, v33
	v_mov_b32_e32 v37, v38
	v_pk_add_f32 v[34:35], v[34:35], v[36:37]
	v_mul_f32_e32 v36, v21, v21
	v_mul_f32_e32 v39, v18, v18
	v_pk_fma_f32 v[36:37], v[20:21], v[20:21], v[36:37] op_sel_hi:[1,1,0]
	v_mul_f32_e32 v38, v23, v23
	v_mul_f32_e32 v40, v19, v19
	v_mov_b32_e32 v37, v39
	v_pk_fma_f32 v[38:39], v[22:23], v[22:23], v[38:39] op_sel_hi:[1,1,0]
	s_nop 0
	v_mov_b32_e32 v39, v40
	v_pk_add_f32 v[36:37], v[36:37], v[38:39]
	s_nop 0
	v_pk_add_f32 v[34:35], v[34:35], v[36:37]
	s_nop 0
	v_add_f32_e32 v33, v34, v35
	ds_bpermute_b32 v34, v173, v33
	s_waitcnt lgkmcnt(0)
	v_add_f32_e32 v33, v33, v34
	ds_bpermute_b32 v34, v174, v33
	s_waitcnt lgkmcnt(0)
	v_add_f32_e32 v33, v33, v34
	v_fmamk_f32 v33, v33, 0x3c800000, v178
	v_mul_f32_e32 v34, 0x4b800000, v33
	v_cmp_gt_f32_e32 vcc, s81, v33
	s_nop 1
	v_cndmask_b32_e32 v33, v33, v34, vcc
	v_rsq_f32_e32 v33, v33
	s_nop 0
	v_mul_f32_e32 v34, 0x45800000, v33
	v_cndmask_b32_e32 v36, v33, v34, vcc
.LBB0_141:
	v_lshlrev_b64 v[34:35], 12, v[164:165]
	v_pk_mul_f32 v[28:29], v[28:29], v[36:37] op_sel_hi:[1,0]
	v_lshl_add_u64 v[34:35], v[166:167], 0, v[34:35]
	v_pk_mul_f32 v[28:29], v[150:151], v[28:29]
	v_pk_mul_f32 v[26:27], v[26:27], v[36:37] op_sel_hi:[1,0]
	v_pk_mul_f32 v[24:25], v[24:25], v[36:37] op_sel_hi:[1,0]
	v_pk_mul_f32 v[30:31], v[30:31], v[36:37] op_sel_hi:[1,0]
	v_pk_mul_f32 v[40:41], v[156:157], v[26:27]
	v_pk_mul_f32 v[26:27], v[148:149], v[24:25]
	v_cvt_pk_bf16_f32 v24, v28, v29
	v_add_co_u32_e32 v28, vcc, s85, v34
	v_pk_mul_f32 v[30:31], v[152:153], v[30:31]
	s_nop 0
	v_addc_co_u32_e32 v29, vcc, 0, v35, vcc
	v_cvt_pk_bf16_f32 v25, v30, v31
	v_pk_mul_f32 v[18:19], v[18:19], v[36:37] op_sel_hi:[1,0]
	v_pk_mul_f32 v[16:17], v[16:17], v[36:37] op_sel_hi:[1,0]
	v_lshl_add_u64 v[38:39], v[34:35], 0, s[38:39]
	v_cvt_pk_bf16_f32 v26, v26, v27
	v_cvt_pk_bf16_f32 v27, v40, v41
	v_mov_b32_e32 v240, v24
	v_mov_b32_e32 v241, v25
	v_mov_b32_e32 v242, v26
	v_mov_b32_e32 v243, v27
	v_pk_mul_f32 v[22:23], v[22:23], v[36:37] op_sel_hi:[1,0]
	v_pk_mul_f32 v[20:21], v[20:21], v[36:37] op_sel_hi:[1,0]
	v_pk_mul_f32 v[24:25], v[162:163], v[18:19]
	v_pk_mul_f32 v[18:19], v[154:155], v[16:17]
	s_and_b64 vcc, exec, s[6:7]
	v_pk_mul_f32 v[22:23], v[160:161], v[22:23]
	v_pk_mul_f32 v[20:21], v[158:159], v[20:21]
	s_nop 0
	v_cvt_pk_bf16_f32 v16, v20, v21
	v_cvt_pk_bf16_f32 v17, v22, v23
	v_cvt_pk_bf16_f32 v18, v18, v19
	v_cvt_pk_bf16_f32 v19, v24, v25
	v_mov_b32_e32 v244, v16
	v_mov_b32_e32 v245, v17
	v_mov_b32_e32 v246, v18
	v_mov_b32_e32 v247, v19
	v_mov_b32_dpp v244, v240 row_shl:8 row_mask:0xf bank_mask:0x3
	v_mov_b32_dpp v245, v241 row_shl:8 row_mask:0xf bank_mask:0x3
	v_mov_b32_dpp v246, v242 row_shl:8 row_mask:0xf bank_mask:0x3
	v_mov_b32_dpp v247, v243 row_shl:8 row_mask:0xf bank_mask:0x3
	v_mov_b32_dpp v240, v16 row_shr:8 row_mask:0xf bank_mask:0xc
	v_mov_b32_dpp v241, v17 row_shr:8 row_mask:0xf bank_mask:0xc
	v_mov_b32_dpp v242, v18 row_shr:8 row_mask:0xf bank_mask:0xc
	v_mov_b32_dpp v243, v19 row_shr:8 row_mask:0xf bank_mask:0xc
	v_lshl_add_u64 v[252:253], v[28:29], 0, v[248:249]
	v_lshl_add_u64 v[254:255], v[28:29], 0, v[250:251]
	global_store_dwordx4 v[252:253], v[240:243], off nt
	global_store_dwordx4 v[254:255], v[244:247], off nt
	s_cbranch_vccnz .LBB0_143
	s_nop 0
	v_pk_mul_f32 v[16:17], v[14:15], v[14:15]
	v_pk_mul_f32 v[18:19], v[12:13], v[12:13]
	s_nop 0
	v_pk_mov_b32 v[20:21], v[18:19], v[16:17] op_sel:[1,0]
	v_mov_b32_e32 v19, v17
	v_pk_add_f32 v[16:17], v[20:21], v[18:19]
	v_pk_mul_f32 v[18:19], v[10:11], v[10:11]
	v_pk_mul_f32 v[20:21], v[8:9], v[8:9]
	v_pk_add_f32 v[16:17], v[16:17], v[16:17] op_sel:[0,1] op_sel_hi:[1,0]
	v_pk_mov_b32 v[22:23], v[20:21], v[18:19] op_sel:[1,0]
	v_mov_b32_e32 v21, v19
	v_pk_add_f32 v[18:19], v[22:23], v[20:21]
	v_mul_f32_e32 v20, v0, v0
	v_mul_f32_e32 v21, v1, v1
	v_pk_add_f32 v[18:19], v[18:19], v[18:19] op_sel:[0,1] op_sel_hi:[1,0]
	v_mov_b32_e32 v17, v20
	v_mov_b32_e32 v19, v21
	v_pk_add_f32 v[16:17], v[16:17], v[18:19]
	v_mul_f32_e32 v18, v5, v5
	v_mul_f32_e32 v20, v7, v7
	v_mul_f32_e32 v22, v2, v2
	v_mul_f32_e32 v23, v3, v3
	v_pk_fma_f32 v[18:19], v[4:5], v[4:5], v[18:19] op_sel_hi:[1,1,0]
	v_pk_fma_f32 v[20:21], v[6:7], v[6:7], v[20:21] op_sel_hi:[1,1,0]
	v_mov_b32_e32 v19, v22
	v_mov_b32_e32 v21, v23
	v_pk_add_f32 v[18:19], v[18:19], v[20:21]
	s_nop 0
	v_pk_add_f32 v[16:17], v[16:17], v[18:19]
	s_nop 0
	v_add_f32_e32 v16, v16, v17
	ds_bpermute_b32 v17, v173, v16
	s_waitcnt lgkmcnt(0)
	v_add_f32_e32 v16, v16, v17
	ds_bpermute_b32 v17, v174, v16
	s_waitcnt lgkmcnt(0)
	v_add_f32_e32 v16, v16, v17
	v_fmamk_f32 v16, v16, 0x3c800000, v178
	v_mul_f32_e32 v17, 0x4b800000, v16
	v_cmp_gt_f32_e32 vcc, s81, v16
	s_nop 1
	v_cndmask_b32_e32 v16, v16, v17, vcc
	v_rsq_f32_e32 v16, v16
	s_nop 0
	v_mul_f32_e32 v17, 0x45800000, v16
	v_cndmask_b32_e32 v32, v16, v17, vcc
; __device__ __forceinline__ u32x4 pack8(const f32x4& a, const f32x4& b) { u32x4 w; w.x = pk2(a[0], a[1]); w.y = pk2(a[2], a[3]); w.z = pk2(b[0], b[1]); w.w = pk2(b[2], b[3]); return w; }
; template <class Epi, class Sched, bool ALIGN_EPI = false, bool SP2 = false>
; __device__ __forceinline__ void gemm_phase(PG8_LAS unsigned char* lds, const Gemm g, const Sched& S, const Epi& E, int tid_in) {
;     ...
;         if constexpr (!Epi::AFTER_DRAIN) { E(acc, cur, wr, wc, fr, fq); S.done(cur); }
;         if (!has_next) break;
;     __device__ __forceinline__ void operator()(const AccT& acc, const Unit& u, int wr, int wc, int fr, int fq) const {
;     ...
;                 bf16_t* rp = base + (size_t)row * BR + tile * 256 + 64 * wc + 8 * fq;
; #pragma unroll
;                 for (int bj = 0; bj < 2; ++bj) { const f32x4 v0 = acc[ai][bj][m][0] * rs * gv[bj][0], v1 = acc[ai][bj][m][1] * rs * gv[bj][1];
;                     __builtin_nontemporal_store(pack8(v0, v1), (u32x4*)(rp + 32 * bj)); }
.LBB0_143:
	v_pk_mul_f32 v[12:13], v[12:13], v[32:33] op_sel_hi:[1,0]
	v_pk_mul_f32 v[10:11], v[10:11], v[32:33] op_sel_hi:[1,0]
	v_pk_mul_f32 v[12:13], v[150:151], v[12:13]
	v_pk_mul_f32 v[8:9], v[8:9], v[32:33] op_sel_hi:[1,0]
	v_pk_mul_f32 v[14:15], v[14:15], v[32:33] op_sel_hi:[1,0]
	v_pk_mul_f32 v[18:19], v[156:157], v[10:11]
	v_pk_mul_f32 v[10:11], v[148:149], v[8:9]
	v_cvt_pk_bf16_f32 v8, v12, v13
	v_add_co_u32_e32 v12, vcc, s86, v34
	v_pk_mul_f32 v[14:15], v[152:153], v[14:15]
	s_nop 0
	v_addc_co_u32_e32 v13, vcc, 0, v35, vcc
	v_cvt_pk_bf16_f32 v9, v14, v15
	v_pk_mul_f32 v[2:3], v[2:3], v[32:33] op_sel_hi:[1,0]
	v_pk_mul_f32 v[0:1], v[0:1], v[32:33] op_sel_hi:[1,0]
	v_lshl_add_u64 v[16:17], v[34:35], 0, s[40:41]
	v_cvt_pk_bf16_f32 v10, v10, v11
	v_cvt_pk_bf16_f32 v11, v18, v19
	v_mov_b32_e32 v240, v8
	v_mov_b32_e32 v241, v9
	v_mov_b32_e32 v242, v10
	v_mov_b32_e32 v243, v11
	v_pk_mul_f32 v[6:7], v[6:7], v[32:33] op_sel_hi:[1,0]
	v_pk_mul_f32 v[4:5], v[4:5], v[32:33] op_sel_hi:[1,0]
	v_pk_mul_f32 v[8:9], v[162:163], v[2:3]
	v_pk_mul_f32 v[2:3], v[154:155], v[0:1]
	s_andn2_b64 vcc, exec, s[0:1]
	s_mov_b64 s[0:1], -1
	v_pk_mul_f32 v[6:7], v[160:161], v[6:7]
	v_pk_mul_f32 v[4:5], v[158:159], v[4:5]
	s_nop 0
	v_cvt_pk_bf16_f32 v0, v4, v5
	v_cvt_pk_bf16_f32 v1, v6, v7
	v_cvt_pk_bf16_f32 v2, v2, v3
	v_cvt_pk_bf16_f32 v3, v8, v9
	v_mov_b32_e32 v244, v0
	v_mov_b32_e32 v245, v1
	v_mov_b32_e32 v246, v2
	v_mov_b32_e32 v247, v3
	v_mov_b32_dpp v244, v240 row_shl:8 row_mask:0xf bank_mask:0x3
	v_mov_b32_dpp v245, v241 row_shl:8 row_mask:0xf bank_mask:0x3
	v_mov_b32_dpp v246, v242 row_shl:8 row_mask:0xf bank_mask:0x3
	v_mov_b32_dpp v247, v243 row_shl:8 row_mask:0xf bank_mask:0x3
	v_mov_b32_dpp v240, v0 row_shr:8 row_mask:0xf bank_mask:0xc
	v_mov_b32_dpp v241, v1 row_shr:8 row_mask:0xf bank_mask:0xc
	v_mov_b32_dpp v242, v2 row_shr:8 row_mask:0xf bank_mask:0xc
	v_mov_b32_dpp v243, v3 row_shr:8 row_mask:0xf bank_mask:0xc
	v_lshl_add_u64 v[252:253], v[12:13], 0, v[248:249]
	v_lshl_add_u64 v[254:255], v[12:13], 0, v[250:251]
	global_store_dwordx4 v[252:253], v[240:243], off nt
	global_store_dwordx4 v[254:255], v[244:247], off nt
	s_cbranch_vccnz .LBB0_108
	s_andn2_b64 vcc, exec, s[8:9]
	s_cbranch_vccnz .LBB0_107
	s_barrier
	s_branch .LBB0_107

;     __device__ __forceinline__ void operator()(const AccT& acc, const Unit& u, int wr, int wc, int fr, int fq) const {
;         const int kind = (u.pn + pn_off) >> 3, tile = (u.pn + pn_off) & 7;
;         bf16_t* base = Q + (size_t)kind * ((WS_K - WS_Q) / 2); if (kind == 2) base = Z;
;         const float* g = gq; if (kind == 1) g = gk; const float gs = kind == 0 ? C2 : 1.f;
;         f32x4 gv[2][2];
; #pragma unroll
;         for (int bj = 0; bj < 2; ++bj)
; #pragma unroll
;             for (int n = 0; n < 2; ++n) gv[bj][n] = (kind < 2) ? *(const f32x4*)(g + 32 * bj + 8 * fq + 4 * n) * gs : (f32x4){1.f, 1.f, 1.f, 1.f};
.LBB0_169:
	v_and_b32_e32 v248, 8, v215
	v_lshrrev_b32_e32 v248, 3, v248
	v_mul_i32_i24_e32 v248, 0xffff8040, v248
	v_ashrrev_i32_e32 v249, 31, v248
	v_add_u32_e32 v250, 0x8000, v248
	v_mov_b32_e32 v251, 0
	s_add_i32 s53, s66, 16
	s_ashr_i32 s70, s53, 3
	s_cmp_eq_u32 s70, 1
	s_cselect_b32 s7, s21, s19
	s_cselect_b32 s6, s20, s18
	s_cmp_lt_u32 s53, 8
	s_cselect_b64 vcc, -1, 0
	v_cndmask_b32_e32 v164, 1.0, v179, vcc
	s_cmp_lt_i32 s70, 2
	v_mov_b32_e32 v148, 1.0
	s_cselect_b64 s[72:73], -1, 0
	s_cmp_gt_i32 s70, 1
	v_mov_b32_e32 v165, v164
	v_lshl_add_u64 v[166:167], s[6:7], 0, v[136:137]
	v_mov_b32_e32 v150, 1.0
	v_mov_b32_e32 v151, 1.0
	v_mov_b32_e32 v152, 1.0
	v_mov_b32_e32 v153, 1.0
	s_cbranch_scc1 .LBB0_171
	global_load_dwordx4 v[150:153], v[166:167], off
	v_mov_b32_e32 v154, v164
	v_mov_b32_e32 v155, v164
	s_waitcnt vmcnt(0)
	v_pk_mul_f32 v[152:153], v[154:155], v[152:153]
	v_pk_mul_f32 v[150:151], v[164:165], v[150:151]

; __device__ __forceinline__ u32x4 pack8(const f32x4& a, const f32x4& b) { u32x4 w; w.x = pk2(a[0], a[1]); w.y = pk2(a[2], a[3]); w.z = pk2(b[0], b[1]); w.w = pk2(b[2], b[3]); return w; }
;     __device__ __forceinline__ void operator()(const AccT& acc, const Unit& u, int wr, int wc, int fr, int fq) const {
;     ...
;         const int row0 = u.pm * 256 + wr * 64 + fr;
; #pragma unroll
;         for (int ai = 0; ai < 2; ++ai)
; #pragma unroll
;             for (int m = 0; m < 4; ++m) {
;                 const int row = row0 + ai * 128 + m * 16; float rs = 1.f;
;                 if (kind < 2) { float ss = 0.f;
; #pragma unroll
;                     for (int bj = 0; bj < 2; ++bj)
; #pragma unroll
;                         for (int n = 0; n < 2; ++n) { const f32x4 v = acc[ai][bj][m][n]; ss += (v[0] * v[0] + v[1] * v[1]) + (v[2] * v[2] + v[3] * v[3]); }
;                     ss += __shfl_xor(ss, 16); ss += __shfl_xor(ss, 32); rs = rsqrtf(ss * (1.f / 64.f) + EPS); }
;                 bf16_t* rp = base + (size_t)row * BR + tile * 256 + 64 * wc + 8 * fq;
; #pragma unroll
;                 for (int bj = 0; bj < 2; ++bj) { const f32x4 v0 = acc[ai][bj][m][0] * rs * gv[bj][0], v1 = acc[ai][bj][m][1] * rs * gv[bj][1];
;                     __builtin_nontemporal_store(pack8(v0, v1), (u32x4*)(rp + 32 * bj)); }
.LBB0_179:
	s_ashr_i32 s71, s70, 31
	s_lshl_b64 s[72:73], s[70:71], 27
	s_add_u32 s53, s34, s72
	s_addc_u32 s59, s35, s73
	s_cmp_eq_u32 s70, 2
	s_cselect_b32 s59, s29, s59
	s_cselect_b32 s53, s28, s53
	v_lshl_add_u32 v164, s64, 8, v139
	s_lshl_b32 s64, s66, 9
	s_and_b32 s64, s64, 0xe00
	s_add_u32 s53, s53, s64
	s_addc_u32 s59, s59, 0
	s_add_u32 s70, s53, s86
	s_addc_u32 s71, s59, 0
	v_lshlrev_b32_e32 v166, 1, v138
	v_mov_b32_e32 v167, v137
	v_ashrrev_i32_e32 v165, 31, v164
	v_lshl_add_u64 v[166:167], s[70:71], 0, v[166:167]
	v_lshlrev_b64 v[180:181], 12, v[164:165]
	v_pk_mul_f32 v[126:127], v[126:127], v[170:171] op_sel_hi:[1,0]
	v_pk_mul_f32 v[124:125], v[124:125], v[170:171] op_sel_hi:[1,0]
	v_pk_mul_f32 v[122:123], v[122:123], v[170:171] op_sel_hi:[1,0]
	v_pk_mul_f32 v[120:121], v[120:121], v[170:171] op_sel_hi:[1,0]
	v_lshl_add_u64 v[180:181], v[166:167], 0, v[180:181]
	v_pk_mul_f32 v[126:127], v[152:153], v[126:127]
	v_pk_mul_f32 v[124:125], v[150:151], v[124:125]
	v_pk_mul_f32 v[182:183], v[156:157], v[122:123]
	v_pk_mul_f32 v[122:123], v[148:149], v[120:121]
	v_cvt_pk_bf16_f32 v120, v124, v125
	v_cvt_pk_bf16_f32 v121, v126, v127
	v_pk_mul_f32 v[114:115], v[114:115], v[170:171] op_sel_hi:[1,0]
	v_pk_mul_f32 v[112:113], v[112:113], v[170:171] op_sel_hi:[1,0]
	v_cvt_pk_bf16_f32 v122, v122, v123
	v_cvt_pk_bf16_f32 v123, v182, v183
	v_mov_b32_e32 v240, v120
	v_mov_b32_e32 v241, v121
	v_mov_b32_e32 v242, v122
	v_mov_b32_e32 v243, v123
	v_pk_mul_f32 v[118:119], v[118:119], v[170:171] op_sel_hi:[1,0]
	v_pk_mul_f32 v[116:117], v[116:117], v[170:171] op_sel_hi:[1,0]
	v_pk_mul_f32 v[120:121], v[162:163], v[114:115]
	v_pk_mul_f32 v[114:115], v[154:155], v[112:113]
	s_and_b64 vcc, exec, s[6:7]
	v_pk_mul_f32 v[118:119], v[160:161], v[118:119]
	v_pk_mul_f32 v[116:117], v[158:159], v[116:117]
	s_nop 0
	v_cvt_pk_bf16_f32 v112, v116, v117
	v_cvt_pk_bf16_f32 v113, v118, v119
	v_cvt_pk_bf16_f32 v114, v114, v115
	v_cvt_pk_bf16_f32 v115, v120, v121
	v_mov_b32_e32 v244, v112
	v_mov_b32_e32 v245, v113
	v_mov_b32_e32 v246, v114
	v_mov_b32_e32 v247, v115
	v_mov_b32_dpp v244, v240 row_shl:8 row_mask:0xf bank_mask:0x3
	v_mov_b32_dpp v245, v241 row_shl:8 row_mask:0xf bank_mask:0x3
	v_mov_b32_dpp v246, v242 row_shl:8 row_mask:0xf bank_mask:0x3
	v_mov_b32_dpp v247, v243 row_shl:8 row_mask:0xf bank_mask:0x3
	v_mov_b32_dpp v240, v112 row_shr:8 row_mask:0xf bank_mask:0xc
	v_mov_b32_dpp v241, v113 row_shr:8 row_mask:0xf bank_mask:0xc
	v_mov_b32_dpp v242, v114 row_shr:8 row_mask:0xf bank_mask:0xc
	v_mov_b32_dpp v243, v115 row_shr:8 row_mask:0xf bank_mask:0xc
	v_lshl_add_u64 v[252:253], v[180:181], 0, v[248:249]
	v_lshl_add_u64 v[254:255], v[180:181], 0, v[250:251]
	global_store_dwordx4 v[252:253], v[240:243], off nt
	global_store_dwordx4 v[254:255], v[244:247], off nt
	s_cbranch_vccnz .LBB0_181
	s_nop 0
	v_pk_mul_f32 v[112:113], v[110:111], v[110:111]
	v_pk_mul_f32 v[114:115], v[108:109], v[108:109]
	s_nop 0
	v_pk_mov_b32 v[116:117], v[114:115], v[112:113] op_sel:[1,0]
	v_mov_b32_e32 v115, v113
	v_pk_add_f32 v[112:113], v[116:117], v[114:115]
	v_pk_mul_f32 v[114:115], v[106:107], v[106:107]
	v_pk_mul_f32 v[116:117], v[104:105], v[104:105]
	v_pk_add_f32 v[112:113], v[112:113], v[112:113] op_sel:[0,1] op_sel_hi:[1,0]
	v_pk_mov_b32 v[118:119], v[116:117], v[114:115] op_sel:[1,0]
	v_mov_b32_e32 v117, v115
	v_pk_add_f32 v[114:115], v[118:119], v[116:117]
	v_mul_f32_e32 v116, v96, v96
	v_mul_f32_e32 v117, v97, v97
	v_pk_add_f32 v[114:115], v[114:115], v[114:115] op_sel:[0,1] op_sel_hi:[1,0]
	v_mov_b32_e32 v113, v116
	v_mov_b32_e32 v115, v117
	v_pk_add_f32 v[112:113], v[112:113], v[114:115]
	v_mul_f32_e32 v114, v101, v101
	v_mul_f32_e32 v116, v103, v103
	v_mul_f32_e32 v118, v98, v98
	v_mul_f32_e32 v119, v99, v99
	v_pk_fma_f32 v[114:115], v[100:101], v[100:101], v[114:115] op_sel_hi:[1,1,0]
	v_pk_fma_f32 v[116:117], v[102:103], v[102:103], v[116:117] op_sel_hi:[1,1,0]
	v_mov_b32_e32 v115, v118
	v_mov_b32_e32 v117, v119
	v_pk_add_f32 v[114:115], v[114:115], v[116:117]
	s_nop 0
	v_pk_add_f32 v[112:113], v[112:113], v[114:115]
	s_nop 0
	v_add_f32_e32 v112, v112, v113
	ds_bpermute_b32 v113, v173, v112
	s_waitcnt lgkmcnt(0)
	v_add_f32_e32 v112, v112, v113
	ds_bpermute_b32 v113, v174, v112
	s_waitcnt lgkmcnt(0)
	v_add_f32_e32 v112, v112, v113
	v_fmamk_f32 v112, v112, 0x3c800000, v178
	v_mul_f32_e32 v113, 0x4b800000, v112
	v_cmp_gt_f32_e32 vcc, s85, v112
	s_nop 1
	v_cndmask_b32_e32 v112, v112, v113, vcc
	v_rsq_f32_e32 v112, v112
	s_nop 0
	v_mul_f32_e32 v113, 0x45800000, v112
	v_cndmask_b32_e32 v168, v112, v113, vcc
; __device__ __forceinline__ u32x4 pack8(const f32x4& a, const f32x4& b) { u32x4 w; w.x = pk2(a[0], a[1]); w.y = pk2(a[2], a[3]); w.z = pk2(b[0], b[1]); w.w = pk2(b[2], b[3]); return w; }
;     __device__ __forceinline__ void operator()(const AccT& acc, const Unit& u, int wr, int wc, int fr, int fq) const {
;     ...
;             for (int m = 0; m < 4; ++m) {
;                 const int row = row0 + ai * 128 + m * 16; float rs = 1.f;
;                 if (kind < 2) { float ss = 0.f;
; #pragma unroll
;                     for (int bj = 0; bj < 2; ++bj)
; #pragma unroll
;                         for (int n = 0; n < 2; ++n) { const f32x4 v = acc[ai][bj][m][n]; ss += (v[0] * v[0] + v[1] * v[1]) + (v[2] * v[2] + v[3] * v[3]); }
;                     ss += __shfl_xor(ss, 16); ss += __shfl_xor(ss, 32); rs = rsqrtf(ss * (1.f / 64.f) + EPS); }
;                 bf16_t* rp = base + (size_t)row * BR + tile * 256 + 64 * wc + 8 * fq;
; #pragma unroll
;                 for (int bj = 0; bj < 2; ++bj) { const f32x4 v0 = acc[ai][bj][m][0] * rs * gv[bj][0], v1 = acc[ai][bj][m][1] * rs * gv[bj][1];
;                     __builtin_nontemporal_store(pack8(v0, v1), (u32x4*)(rp + 32 * bj)); }
.LBB0_181:
	s_nop 0
	v_or_b32_e32 v112, 16, v164
	v_ashrrev_i32_e32 v113, 31, v112
	v_lshlrev_b64 v[112:113], 12, v[112:113]
	v_pk_mul_f32 v[110:111], v[110:111], v[168:169] op_sel_hi:[1,0]
	v_pk_mul_f32 v[108:109], v[108:109], v[168:169] op_sel_hi:[1,0]
	v_pk_mul_f32 v[106:107], v[106:107], v[168:169] op_sel_hi:[1,0]
	v_pk_mul_f32 v[104:105], v[104:105], v[168:169] op_sel_hi:[1,0]
	v_lshl_add_u64 v[112:113], v[166:167], 0, v[112:113]
	v_pk_mul_f32 v[110:111], v[152:153], v[110:111]
	v_pk_mul_f32 v[108:109], v[150:151], v[108:109]
	v_pk_mul_f32 v[114:115], v[156:157], v[106:107]
	v_pk_mul_f32 v[106:107], v[148:149], v[104:105]
	v_cvt_pk_bf16_f32 v104, v108, v109
	v_cvt_pk_bf16_f32 v105, v110, v111
	v_pk_mul_f32 v[98:99], v[98:99], v[168:169] op_sel_hi:[1,0]
	v_pk_mul_f32 v[96:97], v[96:97], v[168:169] op_sel_hi:[1,0]
	v_cvt_pk_bf16_f32 v106, v106, v107
	v_cvt_pk_bf16_f32 v107, v114, v115
	v_mov_b32_e32 v240, v104
	v_mov_b32_e32 v241, v105
	v_mov_b32_e32 v242, v106
	v_mov_b32_e32 v243, v107
	v_pk_mul_f32 v[102:103], v[102:103], v[168:169] op_sel_hi:[1,0]
	v_pk_mul_f32 v[100:101], v[100:101], v[168:169] op_sel_hi:[1,0]
	v_pk_mul_f32 v[104:105], v[162:163], v[98:99]
	v_pk_mul_f32 v[98:99], v[154:155], v[96:97]
	v_pk_mul_f32 v[102:103], v[160:161], v[102:103]
	v_pk_mul_f32 v[100:101], v[158:159], v[100:101]
	s_and_b64 vcc, exec, s[6:7]
	v_cvt_pk_bf16_f32 v96, v100, v101
	v_cvt_pk_bf16_f32 v97, v102, v103
	v_cvt_pk_bf16_f32 v98, v98, v99
	v_cvt_pk_bf16_f32 v99, v104, v105
	v_mov_b32_e32 v244, v96
	v_mov_b32_e32 v245, v97
	v_mov_b32_e32 v246, v98
	v_mov_b32_e32 v247, v99
	v_mov_b32_dpp v244, v240 row_shl:8 row_mask:0xf bank_mask:0x3
	v_mov_b32_dpp v245, v241 row_shl:8 row_mask:0xf bank_mask:0x3
	v_mov_b32_dpp v246, v242 row_shl:8 row_mask:0xf bank_mask:0x3
	v_mov_b32_dpp v247, v243 row_shl:8 row_mask:0xf bank_mask:0x3
	v_mov_b32_dpp v240, v96 row_shr:8 row_mask:0xf bank_mask:0xc
	v_mov_b32_dpp v241, v97 row_shr:8 row_mask:0xf bank_mask:0xc
	v_mov_b32_dpp v242, v98 row_shr:8 row_mask:0xf bank_mask:0xc
	v_mov_b32_dpp v243, v99 row_shr:8 row_mask:0xf bank_mask:0xc
	v_lshl_add_u64 v[252:253], v[112:113], 0, v[248:249]
	v_lshl_add_u64 v[254:255], v[112:113], 0, v[250:251]
	global_store_dwordx4 v[252:253], v[240:243], off nt
	global_store_dwordx4 v[254:255], v[244:247], off nt
	s_nop 1
	v_mov_b32_e32 v96, 1.0
	v_mov_b32_e32 v98, 1.0
	s_cbranch_vccnz .LBB0_183
	v_pk_mul_f32 v[98:99], v[94:95], v[94:95]
	v_pk_mul_f32 v[100:101], v[92:93], v[92:93]
	v_mul_f32_e32 v97, v80, v80
	v_pk_mov_b32 v[102:103], v[100:101], v[98:99] op_sel:[1,0]
	v_mov_b32_e32 v101, v99
	v_pk_add_f32 v[98:99], v[102:103], v[100:101]
	v_pk_mul_f32 v[100:101], v[90:91], v[90:91]
	v_pk_mul_f32 v[102:103], v[88:89], v[88:89]
	v_pk_add_f32 v[98:99], v[98:99], v[98:99] op_sel:[0,1] op_sel_hi:[1,0]
	v_pk_mov_b32 v[104:105], v[102:103], v[100:101] op_sel:[1,0]
	v_mov_b32_e32 v103, v101
	v_pk_add_f32 v[100:101], v[104:105], v[102:103]
	v_mul_f32_e32 v102, v81, v81
	v_pk_add_f32 v[100:101], v[100:101], v[100:101] op_sel:[0,1] op_sel_hi:[1,0]
	v_mov_b32_e32 v99, v97
	v_mov_b32_e32 v101, v102
	v_pk_add_f32 v[98:99], v[98:99], v[100:101]
	v_mul_f32_e32 v100, v85, v85
	v_mul_f32_e32 v103, v82, v82
	v_pk_fma_f32 v[100:101], v[84:85], v[84:85], v[100:101] op_sel_hi:[1,1,0]
	v_mul_f32_e32 v102, v87, v87
	v_mul_f32_e32 v104, v83, v83
	v_mov_b32_e32 v101, v103
	v_pk_fma_f32 v[102:103], v[86:87], v[86:87], v[102:103] op_sel_hi:[1,1,0]
	s_nop 0
	v_mov_b32_e32 v103, v104
	v_pk_add_f32 v[100:101], v[100:101], v[102:103]
	s_nop 0
	v_pk_add_f32 v[98:99], v[98:99], v[100:101]
	s_nop 0
	v_add_f32_e32 v97, v98, v99
	ds_bpermute_b32 v98, v173, v97
	s_waitcnt lgkmcnt(0)
	v_add_f32_e32 v97, v97, v98
	ds_bpermute_b32 v98, v174, v97
	s_waitcnt lgkmcnt(0)
	v_add_f32_e32 v97, v97, v98
	v_fmamk_f32 v97, v97, 0x3c800000, v178
	v_mul_f32_e32 v98, 0x4b800000, v97
	v_cmp_gt_f32_e32 vcc, s85, v97
	s_nop 1
	v_cndmask_b32_e32 v97, v97, v98, vcc
	v_rsq_f32_e32 v97, v97
	s_nop 0
	v_mul_f32_e32 v98, 0x45800000, v97
	v_cndmask_b32_e32 v98, v97, v98, vcc
.LBB0_183:
	v_or_b32_e32 v100, 32, v164
	v_ashrrev_i32_e32 v101, 31, v100
	v_lshlrev_b64 v[100:101], 12, v[100:101]
	v_pk_mul_f32 v[94:95], v[94:95], v[98:99] op_sel_hi:[1,0]
	v_pk_mul_f32 v[92:93], v[92:93], v[98:99] op_sel_hi:[1,0]
	v_pk_mul_f32 v[90:91], v[90:91], v[98:99] op_sel_hi:[1,0]
	v_pk_mul_f32 v[88:89], v[88:89], v[98:99] op_sel_hi:[1,0]
	v_lshl_add_u64 v[100:101], v[166:167], 0, v[100:101]
	v_pk_mul_f32 v[94:95], v[152:153], v[94:95]
	v_pk_mul_f32 v[92:93], v[150:151], v[92:93]
	v_pk_mul_f32 v[102:103], v[156:157], v[90:91]
	v_pk_mul_f32 v[90:91], v[148:149], v[88:89]
	v_cvt_pk_bf16_f32 v88, v92, v93
	v_cvt_pk_bf16_f32 v89, v94, v95
	v_pk_mul_f32 v[82:83], v[82:83], v[98:99] op_sel_hi:[1,0]
	v_pk_mul_f32 v[80:81], v[80:81], v[98:99] op_sel_hi:[1,0]
	v_cvt_pk_bf16_f32 v90, v90, v91
	v_cvt_pk_bf16_f32 v91, v102, v103
	v_mov_b32_e32 v240, v88
	v_mov_b32_e32 v241, v89
	v_mov_b32_e32 v242, v90
	v_mov_b32_e32 v243, v91
	v_pk_mul_f32 v[86:87], v[86:87], v[98:99] op_sel_hi:[1,0]
	v_pk_mul_f32 v[84:85], v[84:85], v[98:99] op_sel_hi:[1,0]
	v_pk_mul_f32 v[88:89], v[162:163], v[82:83]
	v_pk_mul_f32 v[82:83], v[154:155], v[80:81]
	s_and_b64 vcc, exec, s[6:7]
	v_pk_mul_f32 v[86:87], v[160:161], v[86:87]
	v_pk_mul_f32 v[84:85], v[158:159], v[84:85]
	s_nop 0
	v_cvt_pk_bf16_f32 v80, v84, v85
	v_cvt_pk_bf16_f32 v81, v86, v87
	v_cvt_pk_bf16_f32 v82, v82, v83
	v_cvt_pk_bf16_f32 v83, v88, v89
	v_mov_b32_e32 v244, v80
	v_mov_b32_e32 v245, v81
	v_mov_b32_e32 v246, v82
	v_mov_b32_e32 v247, v83
	v_mov_b32_dpp v244, v240 row_shl:8 row_mask:0xf bank_mask:0x3
	v_mov_b32_dpp v245, v241 row_shl:8 row_mask:0xf bank_mask:0x3
	v_mov_b32_dpp v246, v242 row_shl:8 row_mask:0xf bank_mask:0x3
	v_mov_b32_dpp v247, v243 row_shl:8 row_mask:0xf bank_mask:0x3
	v_mov_b32_dpp v240, v80 row_shr:8 row_mask:0xf bank_mask:0xc
	v_mov_b32_dpp v241, v81 row_shr:8 row_mask:0xf bank_mask:0xc
	v_mov_b32_dpp v242, v82 row_shr:8 row_mask:0xf bank_mask:0xc
	v_mov_b32_dpp v243, v83 row_shr:8 row_mask:0xf bank_mask:0xc
	v_lshl_add_u64 v[252:253], v[100:101], 0, v[248:249]
	v_lshl_add_u64 v[254:255], v[100:101], 0, v[250:251]
	global_store_dwordx4 v[252:253], v[240:243], off nt
	global_store_dwordx4 v[254:255], v[244:247], off nt
	s_cbranch_vccnz .LBB0_185
; __device__ __forceinline__ u32x4 pack8(const f32x4& a, const f32x4& b) { u32x4 w; w.x = pk2(a[0], a[1]); w.y = pk2(a[2], a[3]); w.z = pk2(b[0], b[1]); w.w = pk2(b[2], b[3]); return w; }
;     __device__ __forceinline__ void operator()(const AccT& acc, const Unit& u, int wr, int wc, int fr, int fq) const {
;     ...
;             for (int m = 0; m < 4; ++m) {
;                 const int row = row0 + ai * 128 + m * 16; float rs = 1.f;
;                 if (kind < 2) { float ss = 0.f;
; #pragma unroll
;                     for (int bj = 0; bj < 2; ++bj)
; #pragma unroll
;                         for (int n = 0; n < 2; ++n) { const f32x4 v = acc[ai][bj][m][n]; ss += (v[0] * v[0] + v[1] * v[1]) + (v[2] * v[2] + v[3] * v[3]); }
;                     ss += __shfl_xor(ss, 16); ss += __shfl_xor(ss, 32); rs = rsqrtf(ss * (1.f / 64.f) + EPS); }
;                 bf16_t* rp = base + (size_t)row * BR + tile * 256 + 64 * wc + 8 * fq;
; #pragma unroll
;                 for (int bj = 0; bj < 2; ++bj) { const f32x4 v0 = acc[ai][bj][m][0] * rs * gv[bj][0], v1 = acc[ai][bj][m][1] * rs * gv[bj][1];
;                     __builtin_nontemporal_store(pack8(v0, v1), (u32x4*)(rp + 32 * bj)); }
	s_nop 0
	v_pk_mul_f32 v[80:81], v[78:79], v[78:79]
	v_pk_mul_f32 v[82:83], v[76:77], v[76:77]
	s_nop 0
	v_pk_mov_b32 v[84:85], v[82:83], v[80:81] op_sel:[1,0]
	v_mov_b32_e32 v83, v81
	v_pk_add_f32 v[80:81], v[84:85], v[82:83]
	v_pk_mul_f32 v[82:83], v[74:75], v[74:75]
	v_pk_mul_f32 v[84:85], v[72:73], v[72:73]
	v_pk_add_f32 v[80:81], v[80:81], v[80:81] op_sel:[0,1] op_sel_hi:[1,0]
	v_pk_mov_b32 v[86:87], v[84:85], v[82:83] op_sel:[1,0]
	v_mov_b32_e32 v85, v83
	v_pk_add_f32 v[82:83], v[86:87], v[84:85]
	v_mul_f32_e32 v84, v64, v64
	v_mul_f32_e32 v85, v65, v65
	v_pk_add_f32 v[82:83], v[82:83], v[82:83] op_sel:[0,1] op_sel_hi:[1,0]
	v_mov_b32_e32 v81, v84
	v_mov_b32_e32 v83, v85
	v_pk_add_f32 v[80:81], v[80:81], v[82:83]
	v_mul_f32_e32 v82, v69, v69
	v_mul_f32_e32 v84, v71, v71
	v_mul_f32_e32 v86, v66, v66
	v_mul_f32_e32 v87, v67, v67
	v_pk_fma_f32 v[82:83], v[68:69], v[68:69], v[82:83] op_sel_hi:[1,1,0]
	v_pk_fma_f32 v[84:85], v[70:71], v[70:71], v[84:85] op_sel_hi:[1,1,0]
	v_mov_b32_e32 v83, v86
	v_mov_b32_e32 v85, v87
	v_pk_add_f32 v[82:83], v[82:83], v[84:85]
	s_nop 0
	v_pk_add_f32 v[80:81], v[80:81], v[82:83]
	s_nop 0
	v_add_f32_e32 v80, v80, v81
	ds_bpermute_b32 v81, v173, v80
	s_waitcnt lgkmcnt(0)
	v_add_f32_e32 v80, v80, v81
	ds_bpermute_b32 v81, v174, v80
	s_waitcnt lgkmcnt(0)
	v_add_f32_e32 v80, v80, v81
	v_fmamk_f32 v80, v80, 0x3c800000, v178
	v_mul_f32_e32 v81, 0x4b800000, v80
	v_cmp_gt_f32_e32 vcc, s85, v80
	s_nop 1
	v_cndmask_b32_e32 v80, v80, v81, vcc
	v_rsq_f32_e32 v80, v80
	s_nop 0
	v_mul_f32_e32 v81, 0x45800000, v80
	v_cndmask_b32_e32 v96, v80, v81, vcc
.LBB0_185:
	s_nop 0
	v_or_b32_e32 v80, 48, v164
	v_ashrrev_i32_e32 v81, 31, v80
	v_lshlrev_b64 v[80:81], 12, v[80:81]
	v_pk_mul_f32 v[78:79], v[78:79], v[96:97] op_sel_hi:[1,0]
	v_pk_mul_f32 v[76:77], v[76:77], v[96:97] op_sel_hi:[1,0]
	v_pk_mul_f32 v[74:75], v[74:75], v[96:97] op_sel_hi:[1,0]
	v_pk_mul_f32 v[72:73], v[72:73], v[96:97] op_sel_hi:[1,0]
	v_lshl_add_u64 v[80:81], v[166:167], 0, v[80:81]
	v_pk_mul_f32 v[78:79], v[152:153], v[78:79]
	v_pk_mul_f32 v[76:77], v[150:151], v[76:77]
	v_pk_mul_f32 v[82:83], v[156:157], v[74:75]
	v_pk_mul_f32 v[74:75], v[148:149], v[72:73]
	v_cvt_pk_bf16_f32 v72, v76, v77
	v_cvt_pk_bf16_f32 v73, v78, v79
	v_pk_mul_f32 v[68:69], v[68:69], v[96:97] op_sel_hi:[1,0]
	v_pk_mul_f32 v[66:67], v[66:67], v[96:97] op_sel_hi:[1,0]
	v_pk_mul_f32 v[64:65], v[64:65], v[96:97] op_sel_hi:[1,0]
	v_cvt_pk_bf16_f32 v74, v74, v75
	v_cvt_pk_bf16_f32 v75, v82, v83
	v_mov_b32_e32 v240, v72
	v_mov_b32_e32 v241, v73
	v_mov_b32_e32 v242, v74
	v_mov_b32_e32 v243, v75
	v_pk_mul_f32 v[70:71], v[70:71], v[96:97] op_sel_hi:[1,0]
	v_pk_mul_f32 v[68:69], v[158:159], v[68:69]
	v_pk_mul_f32 v[72:73], v[162:163], v[66:67]
	v_pk_mul_f32 v[66:67], v[154:155], v[64:65]
	v_cvt_pk_bf16_f32 v64, v68, v69
	v_pk_mul_f32 v[70:71], v[160:161], v[70:71]
	s_and_b64 vcc, exec, s[6:7]
	v_cvt_pk_bf16_f32 v65, v70, v71
	v_cvt_pk_bf16_f32 v66, v66, v67
	v_cvt_pk_bf16_f32 v67, v72, v73
	v_mov_b32_e32 v244, v64
	v_mov_b32_e32 v245, v65
	v_mov_b32_e32 v246, v66
	v_mov_b32_e32 v247, v67
	v_mov_b32_dpp v244, v240 row_shl:8 row_mask:0xf bank_mask:0x3
	v_mov_b32_dpp v245, v241 row_shl:8 row_mask:0xf bank_mask:0x3
	v_mov_b32_dpp v246, v242 row_shl:8 row_mask:0xf bank_mask:0x3
	v_mov_b32_dpp v247, v243 row_shl:8 row_mask:0xf bank_mask:0x3
	v_mov_b32_dpp v240, v64 row_shr:8 row_mask:0xf bank_mask:0xc
	v_mov_b32_dpp v241, v65 row_shr:8 row_mask:0xf bank_mask:0xc
	v_mov_b32_dpp v242, v66 row_shr:8 row_mask:0xf bank_mask:0xc
	v_mov_b32_dpp v243, v67 row_shr:8 row_mask:0xf bank_mask:0xc
	v_lshl_add_u64 v[252:253], v[80:81], 0, v[248:249]
	v_lshl_add_u64 v[254:255], v[80:81], 0, v[250:251]
	global_store_dwordx4 v[252:253], v[240:243], off nt
	global_store_dwordx4 v[254:255], v[244:247], off nt
	v_mov_b32_e32 v68, 1.0
	s_nop 0
	v_mov_b32_e32 v64, 1.0
	s_cbranch_vccnz .LBB0_187
	v_pk_mul_f32 v[66:67], v[62:63], v[62:63]
	v_pk_mul_f32 v[68:69], v[60:61], v[60:61]
	v_mul_f32_e32 v65, v48, v48
	v_pk_mov_b32 v[70:71], v[68:69], v[66:67] op_sel:[1,0]
	v_mov_b32_e32 v69, v67
	v_pk_add_f32 v[66:67], v[70:71], v[68:69]
	v_pk_mul_f32 v[68:69], v[58:59], v[58:59]
	v_pk_mul_f32 v[70:71], v[56:57], v[56:57]
	v_pk_add_f32 v[66:67], v[66:67], v[66:67] op_sel:[0,1] op_sel_hi:[1,0]
	v_pk_mov_b32 v[72:73], v[70:71], v[68:69] op_sel:[1,0]
	v_mov_b32_e32 v71, v69
	v_pk_add_f32 v[68:69], v[72:73], v[70:71]
	v_mul_f32_e32 v70, v49, v49
	v_pk_add_f32 v[68:69], v[68:69], v[68:69] op_sel:[0,1] op_sel_hi:[1,0]
	v_mov_b32_e32 v67, v65
	v_mov_b32_e32 v69, v70
	v_pk_add_f32 v[66:67], v[66:67], v[68:69]
	v_mul_f32_e32 v68, v53, v53
	v_mul_f32_e32 v71, v50, v50
	v_pk_fma_f32 v[68:69], v[52:53], v[52:53], v[68:69] op_sel_hi:[1,1,0]
	v_mul_f32_e32 v70, v55, v55
	v_mul_f32_e32 v72, v51, v51
	v_mov_b32_e32 v69, v71
	v_pk_fma_f32 v[70:71], v[54:55], v[54:55], v[70:71] op_sel_hi:[1,1,0]
	s_nop 0
	v_mov_b32_e32 v71, v72
	v_pk_add_f32 v[68:69], v[68:69], v[70:71]
	s_nop 0
	v_pk_add_f32 v[66:67], v[66:67], v[68:69]
	s_nop 0
	v_add_f32_e32 v65, v66, v67
	ds_bpermute_b32 v66, v173, v65
	s_waitcnt lgkmcnt(0)
	v_add_f32_e32 v65, v65, v66
	ds_bpermute_b32 v66, v174, v65
	s_waitcnt lgkmcnt(0)
	v_add_f32_e32 v65, v65, v66
	v_fmamk_f32 v65, v65, 0x3c800000, v178
	v_mul_f32_e32 v66, 0x4b800000, v65
	v_cmp_gt_f32_e32 vcc, s85, v65
	s_nop 1
	v_cndmask_b32_e32 v65, v65, v66, vcc
	v_rsq_f32_e32 v65, v65
	s_nop 0
	v_mul_f32_e32 v66, 0x45800000, v65
	v_cndmask_b32_e32 v68, v65, v66, vcc
; __device__ __forceinline__ u32x4 pack8(const f32x4& a, const f32x4& b) { u32x4 w; w.x = pk2(a[0], a[1]); w.y = pk2(a[2], a[3]); w.z = pk2(b[0], b[1]); w.w = pk2(b[2], b[3]); return w; }
;     __device__ __forceinline__ void operator()(const AccT& acc, const Unit& u, int wr, int wc, int fr, int fq) const {
;     ...
;             for (int m = 0; m < 4; ++m) {
;                 const int row = row0 + ai * 128 + m * 16; float rs = 1.f;
;                 if (kind < 2) { float ss = 0.f;
; #pragma unroll
;                     for (int bj = 0; bj < 2; ++bj)
; #pragma unroll
;                         for (int n = 0; n < 2; ++n) { const f32x4 v = acc[ai][bj][m][n]; ss += (v[0] * v[0] + v[1] * v[1]) + (v[2] * v[2] + v[3] * v[3]); }
;                     ss += __shfl_xor(ss, 16); ss += __shfl_xor(ss, 32); rs = rsqrtf(ss * (1.f / 64.f) + EPS); }
;                 bf16_t* rp = base + (size_t)row * BR + tile * 256 + 64 * wc + 8 * fq;
; #pragma unroll
;                 for (int bj = 0; bj < 2; ++bj) { const f32x4 v0 = acc[ai][bj][m][0] * rs * gv[bj][0], v1 = acc[ai][bj][m][1] * rs * gv[bj][1];
;                     __builtin_nontemporal_store(pack8(v0, v1), (u32x4*)(rp + 32 * bj)); }
.LBB0_187:
	v_lshlrev_b64 v[66:67], 12, v[164:165]
	v_pk_mul_f32 v[60:61], v[60:61], v[68:69] op_sel_hi:[1,0]
	v_lshl_add_u64 v[66:67], v[166:167], 0, v[66:67]
	v_pk_mul_f32 v[60:61], v[150:151], v[60:61]
	v_pk_mul_f32 v[58:59], v[58:59], v[68:69] op_sel_hi:[1,0]
	v_pk_mul_f32 v[56:57], v[56:57], v[68:69] op_sel_hi:[1,0]
	v_pk_mul_f32 v[62:63], v[62:63], v[68:69] op_sel_hi:[1,0]
	v_pk_mul_f32 v[72:73], v[156:157], v[58:59]
	v_pk_mul_f32 v[58:59], v[148:149], v[56:57]
	v_cvt_pk_bf16_f32 v56, v60, v61
	v_add_co_u32_e32 v60, vcc, s87, v66
	v_pk_mul_f32 v[62:63], v[152:153], v[62:63]
	s_nop 0
	v_addc_co_u32_e32 v61, vcc, 0, v67, vcc
	v_cvt_pk_bf16_f32 v57, v62, v63
	v_pk_mul_f32 v[50:51], v[50:51], v[68:69] op_sel_hi:[1,0]
	v_pk_mul_f32 v[48:49], v[48:49], v[68:69] op_sel_hi:[1,0]
	v_lshl_add_u64 v[70:71], v[66:67], 0, s[36:37]
	v_cvt_pk_bf16_f32 v58, v58, v59
	v_cvt_pk_bf16_f32 v59, v72, v73
	v_mov_b32_e32 v240, v56
	v_mov_b32_e32 v241, v57
	v_mov_b32_e32 v242, v58
	v_mov_b32_e32 v243, v59
	v_pk_mul_f32 v[54:55], v[54:55], v[68:69] op_sel_hi:[1,0]
	v_pk_mul_f32 v[52:53], v[52:53], v[68:69] op_sel_hi:[1,0]
	v_pk_mul_f32 v[56:57], v[162:163], v[50:51]
	v_pk_mul_f32 v[50:51], v[154:155], v[48:49]
	s_and_b64 vcc, exec, s[6:7]
	v_pk_mul_f32 v[54:55], v[160:161], v[54:55]
	v_pk_mul_f32 v[52:53], v[158:159], v[52:53]
	s_nop 0
	v_cvt_pk_bf16_f32 v48, v52, v53
	v_cvt_pk_bf16_f32 v49, v54, v55
	v_cvt_pk_bf16_f32 v50, v50, v51
	v_cvt_pk_bf16_f32 v51, v56, v57
	v_mov_b32_e32 v244, v48
	v_mov_b32_e32 v245, v49
	v_mov_b32_e32 v246, v50
	v_mov_b32_e32 v247, v51
	v_mov_b32_dpp v244, v240 row_shl:8 row_mask:0xf bank_mask:0x3
	v_mov_b32_dpp v245, v241 row_shl:8 row_mask:0xf bank_mask:0x3
	v_mov_b32_dpp v246, v242 row_shl:8 row_mask:0xf bank_mask:0x3
	v_mov_b32_dpp v247, v243 row_shl:8 row_mask:0xf bank_mask:0x3
	v_mov_b32_dpp v240, v48 row_shr:8 row_mask:0xf bank_mask:0xc
	v_mov_b32_dpp v241, v49 row_shr:8 row_mask:0xf bank_mask:0xc
	v_mov_b32_dpp v242, v50 row_shr:8 row_mask:0xf bank_mask:0xc
	v_mov_b32_dpp v243, v51 row_shr:8 row_mask:0xf bank_mask:0xc
	v_lshl_add_u64 v[252:253], v[60:61], 0, v[248:249]
	v_lshl_add_u64 v[254:255], v[60:61], 0, v[250:251]
	global_store_dwordx4 v[252:253], v[240:243], off nt
	global_store_dwordx4 v[254:255], v[244:247], off nt
	s_cbranch_vccnz .LBB0_189
	s_nop 0
	v_pk_mul_f32 v[48:49], v[46:47], v[46:47]
	v_pk_mul_f32 v[50:51], v[44:45], v[44:45]
	s_nop 0
	v_pk_mov_b32 v[52:53], v[50:51], v[48:49] op_sel:[1,0]
	v_mov_b32_e32 v51, v49
	v_pk_add_f32 v[48:49], v[52:53], v[50:51]
	v_pk_mul_f32 v[50:51], v[42:43], v[42:43]
	v_pk_mul_f32 v[52:53], v[40:41], v[40:41]
	v_pk_add_f32 v[48:49], v[48:49], v[48:49] op_sel:[0,1] op_sel_hi:[1,0]
	v_pk_mov_b32 v[54:55], v[52:53], v[50:51] op_sel:[1,0]
	v_mov_b32_e32 v53, v51
	v_pk_add_f32 v[50:51], v[54:55], v[52:53]
	v_mul_f32_e32 v52, v32, v32
	v_mul_f32_e32 v53, v33, v33
	v_pk_add_f32 v[50:51], v[50:51], v[50:51] op_sel:[0,1] op_sel_hi:[1,0]
	v_mov_b32_e32 v49, v52
	v_mov_b32_e32 v51, v53
	v_pk_add_f32 v[48:49], v[48:49], v[50:51]
	v_mul_f32_e32 v50, v37, v37
	v_mul_f32_e32 v52, v39, v39
	v_mul_f32_e32 v54, v34, v34
	v_mul_f32_e32 v55, v35, v35
	v_pk_fma_f32 v[50:51], v[36:37], v[36:37], v[50:51] op_sel_hi:[1,1,0]
	v_pk_fma_f32 v[52:53], v[38:39], v[38:39], v[52:53] op_sel_hi:[1,1,0]
	v_mov_b32_e32 v51, v54
	v_mov_b32_e32 v53, v55
	v_pk_add_f32 v[50:51], v[50:51], v[52:53]
	s_nop 0
	v_pk_add_f32 v[48:49], v[48:49], v[50:51]
	s_nop 0
	v_add_f32_e32 v48, v48, v49
	ds_bpermute_b32 v49, v173, v48
	s_waitcnt lgkmcnt(0)
	v_add_f32_e32 v48, v48, v49
	ds_bpermute_b32 v49, v174, v48
	s_waitcnt lgkmcnt(0)
	v_add_f32_e32 v48, v48, v49
	v_fmamk_f32 v48, v48, 0x3c800000, v178
	v_mul_f32_e32 v49, 0x4b800000, v48
	v_cmp_gt_f32_e32 vcc, s85, v48
	s_nop 1
	v_cndmask_b32_e32 v48, v48, v49, vcc
	v_rsq_f32_e32 v48, v48
	s_nop 0
	v_mul_f32_e32 v49, 0x45800000, v48
	v_cndmask_b32_e32 v64, v48, v49, vcc
.LBB0_189:
	v_pk_mul_f32 v[44:45], v[44:45], v[64:65] op_sel_hi:[1,0]
	v_pk_mul_f32 v[42:43], v[42:43], v[64:65] op_sel_hi:[1,0]
	v_pk_mul_f32 v[44:45], v[150:151], v[44:45]
	v_pk_mul_f32 v[40:41], v[40:41], v[64:65] op_sel_hi:[1,0]
	v_pk_mul_f32 v[46:47], v[46:47], v[64:65] op_sel_hi:[1,0]
	v_pk_mul_f32 v[50:51], v[156:157], v[42:43]
	v_pk_mul_f32 v[42:43], v[148:149], v[40:41]
	v_cvt_pk_bf16_f32 v40, v44, v45
	v_add_co_u32_e32 v44, vcc, s88, v66
	v_pk_mul_f32 v[46:47], v[152:153], v[46:47]
	s_nop 0
	v_addc_co_u32_e32 v45, vcc, 0, v67, vcc
	v_cvt_pk_bf16_f32 v41, v46, v47
	v_pk_mul_f32 v[36:37], v[36:37], v[64:65] op_sel_hi:[1,0]
	v_pk_mul_f32 v[34:35], v[34:35], v[64:65] op_sel_hi:[1,0]
	v_pk_mul_f32 v[32:33], v[32:33], v[64:65] op_sel_hi:[1,0]
	v_lshl_add_u64 v[48:49], v[66:67], 0, s[38:39]
	v_cvt_pk_bf16_f32 v42, v42, v43
	v_cvt_pk_bf16_f32 v43, v50, v51
	v_mov_b32_e32 v240, v40
	v_mov_b32_e32 v241, v41
	v_mov_b32_e32 v242, v42
	v_mov_b32_e32 v243, v43
	v_pk_mul_f32 v[38:39], v[38:39], v[64:65] op_sel_hi:[1,0]
	v_pk_mul_f32 v[36:37], v[158:159], v[36:37]
	v_pk_mul_f32 v[40:41], v[162:163], v[34:35]
	v_pk_mul_f32 v[34:35], v[154:155], v[32:33]
	v_cvt_pk_bf16_f32 v32, v36, v37
	v_pk_mul_f32 v[38:39], v[160:161], v[38:39]
	s_and_b64 vcc, exec, s[6:7]
	v_cvt_pk_bf16_f32 v33, v38, v39
	v_cvt_pk_bf16_f32 v34, v34, v35
	v_cvt_pk_bf16_f32 v35, v40, v41
	v_mov_b32_e32 v244, v32
	v_mov_b32_e32 v245, v33
	v_mov_b32_e32 v246, v34
	v_mov_b32_e32 v247, v35
	v_mov_b32_dpp v244, v240 row_shl:8 row_mask:0xf bank_mask:0x3
	v_mov_b32_dpp v245, v241 row_shl:8 row_mask:0xf bank_mask:0x3
	v_mov_b32_dpp v246, v242 row_shl:8 row_mask:0xf bank_mask:0x3
	v_mov_b32_dpp v247, v243 row_shl:8 row_mask:0xf bank_mask:0x3
	v_mov_b32_dpp v240, v32 row_shr:8 row_mask:0xf bank_mask:0xc
	v_mov_b32_dpp v241, v33 row_shr:8 row_mask:0xf bank_mask:0xc
	v_mov_b32_dpp v242, v34 row_shr:8 row_mask:0xf bank_mask:0xc
	v_mov_b32_dpp v243, v35 row_shr:8 row_mask:0xf bank_mask:0xc
	v_lshl_add_u64 v[252:253], v[44:45], 0, v[248:249]
	v_lshl_add_u64 v[254:255], v[44:45], 0, v[250:251]
	global_store_dwordx4 v[252:253], v[240:243], off nt
	global_store_dwordx4 v[254:255], v[244:247], off nt
	v_mov_b32_e32 v36, 1.0
	s_nop 0
	v_mov_b32_e32 v32, 1.0
	s_cbranch_vccnz .LBB0_191
; __device__ __forceinline__ u32x4 pack8(const f32x4& a, const f32x4& b) { u32x4 w; w.x = pk2(a[0], a[1]); w.y = pk2(a[2], a[3]); w.z = pk2(b[0], b[1]); w.w = pk2(b[2], b[3]); return w; }
;     __device__ __forceinline__ void operator()(const AccT& acc, const Unit& u, int wr, int wc, int fr, int fq) const {
;     ...
;             for (int m = 0; m < 4; ++m) {
;                 const int row = row0 + ai * 128 + m * 16; float rs = 1.f;
;                 if (kind < 2) { float ss = 0.f;
; #pragma unroll
;                     for (int bj = 0; bj < 2; ++bj)
; #pragma unroll
;                         for (int n = 0; n < 2; ++n) { const f32x4 v = acc[ai][bj][m][n]; ss += (v[0] * v[0] + v[1] * v[1]) + (v[2] * v[2] + v[3] * v[3]); }
;                     ss += __shfl_xor(ss, 16); ss += __shfl_xor(ss, 32); rs = rsqrtf(ss * (1.f / 64.f) + EPS); }
;                 bf16_t* rp = base + (size_t)row * BR + tile * 256 + 64 * wc + 8 * fq;
; #pragma unroll
;                 for (int bj = 0; bj < 2; ++bj) { const f32x4 v0 = acc[ai][bj][m][0] * rs * gv[bj][0], v1 = acc[ai][bj][m][1] * rs * gv[bj][1];
;                     __builtin_nontemporal_store(pack8(v0, v1), (u32x4*)(rp + 32 * bj)); }
	v_pk_mul_f32 v[34:35], v[30:31], v[30:31]
	v_pk_mul_f32 v[36:37], v[28:29], v[28:29]
	v_mul_f32_e32 v33, v16, v16
	v_pk_mov_b32 v[38:39], v[36:37], v[34:35] op_sel:[1,0]
	v_mov_b32_e32 v37, v35
	v_pk_add_f32 v[34:35], v[38:39], v[36:37]
	v_pk_mul_f32 v[36:37], v[26:27], v[26:27]
	v_pk_mul_f32 v[38:39], v[24:25], v[24:25]
	v_pk_add_f32 v[34:35], v[34:35], v[34:35] op_sel:[0,1] op_sel_hi:[1,0]
	v_pk_mov_b32 v[40:41], v[38:39], v[36:37] op_sel:[1,0]
	v_mov_b32_e32 v39, v37
	v_pk_add_f32 v[36:37], v[40:41], v[38:39]
	v_mul_f32_e32 v38, v17, v17
	v_pk_add_f32 v[36:37], v[36:37], v[36:37] op_sel:[0,1] op_sel_hi:[1,0]
	v_mov_b32_e32 v35, v33
	v_mov_b32_e32 v37, v38
	v_pk_add_f32 v[34:35], v[34:35], v[36:37]
	v_mul_f32_e32 v36, v21, v21
	v_mul_f32_e32 v39, v18, v18
	v_pk_fma_f32 v[36:37], v[20:21], v[20:21], v[36:37] op_sel_hi:[1,1,0]
	v_mul_f32_e32 v38, v23, v23
	v_mul_f32_e32 v40, v19, v19
	v_mov_b32_e32 v37, v39
	v_pk_fma_f32 v[38:39], v[22:23], v[22:23], v[38:39] op_sel_hi:[1,1,0]
	s_nop 0
	v_mov_b32_e32 v39, v40
	v_pk_add_f32 v[36:37], v[36:37], v[38:39]
	s_nop 0
	v_pk_add_f32 v[34:35], v[34:35], v[36:37]
	s_nop 0
	v_add_f32_e32 v33, v34, v35
	ds_bpermute_b32 v34, v173, v33
	s_waitcnt lgkmcnt(0)
	v_add_f32_e32 v33, v33, v34
	ds_bpermute_b32 v34, v174, v33
	s_waitcnt lgkmcnt(0)
	v_add_f32_e32 v33, v33, v34
	v_fmamk_f32 v33, v33, 0x3c800000, v178
	v_mul_f32_e32 v34, 0x4b800000, v33
	v_cmp_gt_f32_e32 vcc, s85, v33
	s_nop 1
	v_cndmask_b32_e32 v33, v33, v34, vcc
	v_rsq_f32_e32 v33, v33
	s_nop 0
	v_mul_f32_e32 v34, 0x45800000, v33
	v_cndmask_b32_e32 v36, v33, v34, vcc
.LBB0_191:
	v_lshlrev_b64 v[34:35], 12, v[164:165]
	v_pk_mul_f32 v[28:29], v[28:29], v[36:37] op_sel_hi:[1,0]
	v_lshl_add_u64 v[34:35], v[166:167], 0, v[34:35]
	v_pk_mul_f32 v[28:29], v[150:151], v[28:29]
	v_pk_mul_f32 v[26:27], v[26:27], v[36:37] op_sel_hi:[1,0]
	v_pk_mul_f32 v[24:25], v[24:25], v[36:37] op_sel_hi:[1,0]
	v_pk_mul_f32 v[30:31], v[30:31], v[36:37] op_sel_hi:[1,0]
	v_pk_mul_f32 v[40:41], v[156:157], v[26:27]
	v_pk_mul_f32 v[26:27], v[148:149], v[24:25]
	v_cvt_pk_bf16_f32 v24, v28, v29
	v_add_co_u32_e32 v28, vcc, s89, v34
	v_pk_mul_f32 v[30:31], v[152:153], v[30:31]
	s_nop 0
	v_addc_co_u32_e32 v29, vcc, 0, v35, vcc
	v_cvt_pk_bf16_f32 v25, v30, v31
	v_pk_mul_f32 v[18:19], v[18:19], v[36:37] op_sel_hi:[1,0]
	v_pk_mul_f32 v[16:17], v[16:17], v[36:37] op_sel_hi:[1,0]
	v_lshl_add_u64 v[38:39], v[34:35], 0, s[40:41]
	v_cvt_pk_bf16_f32 v26, v26, v27
	v_cvt_pk_bf16_f32 v27, v40, v41
	v_mov_b32_e32 v240, v24
	v_mov_b32_e32 v241, v25
	v_mov_b32_e32 v242, v26
	v_mov_b32_e32 v243, v27
	v_pk_mul_f32 v[22:23], v[22:23], v[36:37] op_sel_hi:[1,0]
	v_pk_mul_f32 v[20:21], v[20:21], v[36:37] op_sel_hi:[1,0]
	v_pk_mul_f32 v[24:25], v[162:163], v[18:19]
	v_pk_mul_f32 v[18:19], v[154:155], v[16:17]
	s_and_b64 vcc, exec, s[6:7]
	v_pk_mul_f32 v[22:23], v[160:161], v[22:23]
	v_pk_mul_f32 v[20:21], v[158:159], v[20:21]
	s_nop 0
	v_cvt_pk_bf16_f32 v16, v20, v21
	v_cvt_pk_bf16_f32 v17, v22, v23
	v_cvt_pk_bf16_f32 v18, v18, v19
	v_cvt_pk_bf16_f32 v19, v24, v25
	v_mov_b32_e32 v244, v16
	v_mov_b32_e32 v245, v17
	v_mov_b32_e32 v246, v18
	v_mov_b32_e32 v247, v19
	v_mov_b32_dpp v244, v240 row_shl:8 row_mask:0xf bank_mask:0x3
	v_mov_b32_dpp v245, v241 row_shl:8 row_mask:0xf bank_mask:0x3
	v_mov_b32_dpp v246, v242 row_shl:8 row_mask:0xf bank_mask:0x3
	v_mov_b32_dpp v247, v243 row_shl:8 row_mask:0xf bank_mask:0x3
	v_mov_b32_dpp v240, v16 row_shr:8 row_mask:0xf bank_mask:0xc
	v_mov_b32_dpp v241, v17 row_shr:8 row_mask:0xf bank_mask:0xc
	v_mov_b32_dpp v242, v18 row_shr:8 row_mask:0xf bank_mask:0xc
	v_mov_b32_dpp v243, v19 row_shr:8 row_mask:0xf bank_mask:0xc
	v_lshl_add_u64 v[252:253], v[28:29], 0, v[248:249]
	v_lshl_add_u64 v[254:255], v[28:29], 0, v[250:251]
	global_store_dwordx4 v[252:253], v[240:243], off nt
	global_store_dwordx4 v[254:255], v[244:247], off nt
	s_cbranch_vccnz .LBB0_193
	s_nop 0
	v_pk_mul_f32 v[16:17], v[14:15], v[14:15]
	v_pk_mul_f32 v[18:19], v[12:13], v[12:13]
	s_nop 0
	v_pk_mov_b32 v[20:21], v[18:19], v[16:17] op_sel:[1,0]
	v_mov_b32_e32 v19, v17
	v_pk_add_f32 v[16:17], v[20:21], v[18:19]
	v_pk_mul_f32 v[18:19], v[10:11], v[10:11]
	v_pk_mul_f32 v[20:21], v[8:9], v[8:9]
	v_pk_add_f32 v[16:17], v[16:17], v[16:17] op_sel:[0,1] op_sel_hi:[1,0]
	v_pk_mov_b32 v[22:23], v[20:21], v[18:19] op_sel:[1,0]
	v_mov_b32_e32 v21, v19
	v_pk_add_f32 v[18:19], v[22:23], v[20:21]
	v_mul_f32_e32 v20, v0, v0
	v_mul_f32_e32 v21, v1, v1
	v_pk_add_f32 v[18:19], v[18:19], v[18:19] op_sel:[0,1] op_sel_hi:[1,0]
	v_mov_b32_e32 v17, v20
	v_mov_b32_e32 v19, v21
	v_pk_add_f32 v[16:17], v[16:17], v[18:19]
	v_mul_f32_e32 v18, v5, v5
	v_mul_f32_e32 v20, v7, v7
	v_mul_f32_e32 v22, v2, v2
	v_mul_f32_e32 v23, v3, v3
	v_pk_fma_f32 v[18:19], v[4:5], v[4:5], v[18:19] op_sel_hi:[1,1,0]
	v_pk_fma_f32 v[20:21], v[6:7], v[6:7], v[20:21] op_sel_hi:[1,1,0]
	v_mov_b32_e32 v19, v22
	v_mov_b32_e32 v21, v23
	v_pk_add_f32 v[18:19], v[18:19], v[20:21]
	s_nop 0
	v_pk_add_f32 v[16:17], v[16:17], v[18:19]
	s_nop 0
	v_add_f32_e32 v16, v16, v17
	ds_bpermute_b32 v17, v173, v16
	s_waitcnt lgkmcnt(0)
	v_add_f32_e32 v16, v16, v17
	ds_bpermute_b32 v17, v174, v16
	s_waitcnt lgkmcnt(0)
	v_add_f32_e32 v16, v16, v17
	v_fmamk_f32 v16, v16, 0x3c800000, v178
	v_mul_f32_e32 v17, 0x4b800000, v16
	v_cmp_gt_f32_e32 vcc, s85, v16
	s_nop 1
	v_cndmask_b32_e32 v16, v16, v17, vcc
	v_rsq_f32_e32 v16, v16
	s_nop 0
	v_mul_f32_e32 v17, 0x45800000, v16
	v_cndmask_b32_e32 v32, v16, v17, vcc
; __device__ __forceinline__ u32x4 pack8(const f32x4& a, const f32x4& b) { u32x4 w; w.x = pk2(a[0], a[1]); w.y = pk2(a[2], a[3]); w.z = pk2(b[0], b[1]); w.w = pk2(b[2], b[3]); return w; }
; template <class Epi, class Sched, bool ALIGN_EPI = false, bool SP2 = false>
; __device__ __forceinline__ void gemm_phase(PG8_LAS unsigned char* lds, const Gemm g, const Sched& S, const Epi& E, int tid_in) {
;     ...
;         if constexpr (!Epi::AFTER_DRAIN) { E(acc, cur, wr, wc, fr, fq); S.done(cur); }
;         if (!has_next) break;
;     __device__ __forceinline__ void operator()(const AccT& acc, const Unit& u, int wr, int wc, int fr, int fq) const {
;     ...
;                 bf16_t* rp = base + (size_t)row * BR + tile * 256 + 64 * wc + 8 * fq;
; #pragma unroll
;                 for (int bj = 0; bj < 2; ++bj) { const f32x4 v0 = acc[ai][bj][m][0] * rs * gv[bj][0], v1 = acc[ai][bj][m][1] * rs * gv[bj][1];
;                     __builtin_nontemporal_store(pack8(v0, v1), (u32x4*)(rp + 32 * bj)); }
.LBB0_193:
	v_pk_mul_f32 v[12:13], v[12:13], v[32:33] op_sel_hi:[1,0]
	v_pk_mul_f32 v[10:11], v[10:11], v[32:33] op_sel_hi:[1,0]
	v_pk_mul_f32 v[12:13], v[150:151], v[12:13]
	v_pk_mul_f32 v[8:9], v[8:9], v[32:33] op_sel_hi:[1,0]
	v_pk_mul_f32 v[14:15], v[14:15], v[32:33] op_sel_hi:[1,0]
	v_pk_mul_f32 v[18:19], v[156:157], v[10:11]
	v_pk_mul_f32 v[10:11], v[148:149], v[8:9]
	v_cvt_pk_bf16_f32 v8, v12, v13
	v_add_co_u32_e32 v12, vcc, s90, v34
	v_pk_mul_f32 v[14:15], v[152:153], v[14:15]
	s_nop 0
	v_addc_co_u32_e32 v13, vcc, 0, v35, vcc
	v_cvt_pk_bf16_f32 v9, v14, v15
	v_pk_mul_f32 v[2:3], v[2:3], v[32:33] op_sel_hi:[1,0]
	v_pk_mul_f32 v[0:1], v[0:1], v[32:33] op_sel_hi:[1,0]
	v_lshl_add_u64 v[16:17], v[34:35], 0, s[42:43]
	v_cvt_pk_bf16_f32 v10, v10, v11
	v_cvt_pk_bf16_f32 v11, v18, v19
	v_mov_b32_e32 v240, v8
	v_mov_b32_e32 v241, v9
	v_mov_b32_e32 v242, v10
	v_mov_b32_e32 v243, v11
	v_pk_mul_f32 v[6:7], v[6:7], v[32:33] op_sel_hi:[1,0]
	v_pk_mul_f32 v[4:5], v[4:5], v[32:33] op_sel_hi:[1,0]
	v_pk_mul_f32 v[8:9], v[162:163], v[2:3]
	v_pk_mul_f32 v[2:3], v[154:155], v[0:1]
	s_andn2_b64 vcc, exec, s[8:9]
	s_mov_b64 s[6:7], -1
	v_pk_mul_f32 v[6:7], v[160:161], v[6:7]
	v_pk_mul_f32 v[4:5], v[158:159], v[4:5]
	s_nop 0
	v_cvt_pk_bf16_f32 v0, v4, v5
	v_cvt_pk_bf16_f32 v1, v6, v7
	v_cvt_pk_bf16_f32 v2, v2, v3
	v_cvt_pk_bf16_f32 v3, v8, v9
	v_mov_b32_e32 v244, v0
	v_mov_b32_e32 v245, v1
	v_mov_b32_e32 v246, v2
	v_mov_b32_e32 v247, v3
	v_mov_b32_dpp v244, v240 row_shl:8 row_mask:0xf bank_mask:0x3
	v_mov_b32_dpp v245, v241 row_shl:8 row_mask:0xf bank_mask:0x3
	v_mov_b32_dpp v246, v242 row_shl:8 row_mask:0xf bank_mask:0x3
	v_mov_b32_dpp v247, v243 row_shl:8 row_mask:0xf bank_mask:0x3
	v_mov_b32_dpp v240, v0 row_shr:8 row_mask:0xf bank_mask:0xc
	v_mov_b32_dpp v241, v1 row_shr:8 row_mask:0xf bank_mask:0xc
	v_mov_b32_dpp v242, v2 row_shr:8 row_mask:0xf bank_mask:0xc
	v_mov_b32_dpp v243, v3 row_shr:8 row_mask:0xf bank_mask:0xc
	v_lshl_add_u64 v[252:253], v[12:13], 0, v[248:249]
	v_lshl_add_u64 v[254:255], v[12:13], 0, v[250:251]
	global_store_dwordx4 v[252:253], v[240:243], off nt
	global_store_dwordx4 v[254:255], v[244:247], off nt
	s_cbranch_vccnz .LBB0_158
	s_andn2_b64 vcc, exec, s[10:11]
	s_cbranch_vccnz .LBB0_157
	s_barrier
	s_branch .LBB0_157
